# v82 (rotated back edge) + K-loop heads aligned to 8 bytes
# baseline (speedup 1.0000x reference)
.LBB0_266:
	s_xor_b64 s[2:3], s[2:3], -1
	s_mov_b32 s34, s74
	s_add_i32 s74, s74, 1
	s_cmp_lt_u32 s34, 5
	s_mov_b64 s[4:5], s[10:11]
	s_mov_b32 s10, s75
	s_cselect_b64 s[14:15], -1, 0
	s_add_i32 s75, s74, s16
	s_mov_b64 s[12:13], s[8:9]
	s_and_b64 s[8:9], s[14:15], exec
	s_cselect_b32 s8, s75, s10
	s_cselect_b32 s10, s6, s6
	s_ashr_i32 s11, s10, 31
	s_lshl_b64 s[10:11], s[10:11], 19
	s_add_u32 s10, s80, s10
	s_addc_u32 s11, s81, s11
	s_and_b64 s[44:45], s[14:15], exec
	s_cselect_b32 s44, s11, s5
	s_cselect_b32 s45, s10, s4
	s_ashr_i32 s9, s8, 31
	s_lshl_b64 s[8:9], s[8:9], 19
	v_readlane_b32 s47, v255, 14
	s_add_u32 s8, s47, s8
	v_readlane_b32 s47, v255, 15
	s_addc_u32 s9, s47, s9
	s_and_b64 s[14:15], s[14:15], exec
	s_cselect_b32 s47, s9, s13
	s_cselect_b32 s55, s8, s12
	s_add_u32 s4, s4, 0x40080
	s_addc_u32 s5, s5, 0
	s_add_u32 s78, s12, 0x100
	s_addc_u32 s79, s13, 0
	s_mov_b32 s85, -2
	s_waitcnt lgkmcnt(0)
	s_add_i32 s86, 0, 0x10000
	v_add_u32_e32 v0, s86, v150
	v_add_u32_e32 v189, 0x10000, v150
	ds_read_b128 v[142:145], v0
	ds_read_b128 v[146:149], v0 offset:1024
	ds_read_b128 v[152:155], v0 offset:2048
	ds_read_b128 v[156:159], v0 offset:3072
	s_add_u32 s12, s4, 0xfffc0080
	s_addc_u32 s13, s5, -1
	s_cmp_eq_u32 s85, 12
	s_cselect_b32 s15, s44, s13
	s_cselect_b32 s14, s45, s12
	s_cselect_b32 s13, s47, s79
	s_cselect_b32 s12, s55, s78
	s_add_i32 m0, s7, 0xc000
	ds_read_b128 v[160:163], v151
	ds_read_b128 v[164:167], v151 offset:1024
	ds_read_b128 v[168:171], v151 offset:2048
	ds_read_b128 v[172:175], v151 offset:3072
	ds_read_b128 v[176:179], v151 offset:4096
	ds_read_b128 v[180:183], v151 offset:5120
	ds_read_b128 v[184:187], v151 offset:6144
	global_load_lds_dwordx4 v138, s[4:5]
	s_add_i32 m0, s7, 0xe000
	ds_read_b128 v[190:193], v151 offset:7168
	global_load_lds_dwordx4 v140, s[4:5]
	s_waitcnt lgkmcnt(8)
	s_barrier
	s_waitcnt lgkmcnt(0)
	v_mfma_f32_16x16x32_bf16 v[126:129], v[142:145], v[160:163], 0
	v_mfma_f32_16x16x32_bf16 v[122:125], v[152:155], v[160:163], 0
	v_mfma_f32_16x16x32_bf16 v[110:113], v[142:145], v[168:171], 0
	v_mfma_f32_16x16x32_bf16 v[106:109], v[152:155], v[168:171], 0
	v_mfma_f32_16x16x32_bf16 v[94:97], v[142:145], v[176:179], 0
	v_mfma_f32_16x16x32_bf16 v[90:93], v[152:155], v[176:179], 0
	v_mfma_f32_16x16x32_bf16 v[78:81], v[142:145], v[184:187], 0
	v_mfma_f32_16x16x32_bf16 v[74:77], v[152:155], v[184:187], 0
	v_mfma_f32_16x16x32_bf16 v[126:129], v[146:149], v[164:167], v[126:129]
	v_mfma_f32_16x16x32_bf16 v[122:125], v[156:159], v[164:167], v[122:125]
	v_mfma_f32_16x16x32_bf16 v[110:113], v[146:149], v[172:175], v[110:113]
	v_mfma_f32_16x16x32_bf16 v[106:109], v[156:159], v[172:175], v[106:109]
	v_mfma_f32_16x16x32_bf16 v[94:97], v[146:149], v[180:183], v[94:97]
	v_mfma_f32_16x16x32_bf16 v[90:93], v[156:159], v[180:183], v[90:93]
	v_mfma_f32_16x16x32_bf16 v[78:81], v[146:149], v[190:193], v[78:81]
	v_mfma_f32_16x16x32_bf16 v[74:77], v[156:159], v[190:193], v[74:77]
	s_barrier
	s_add_i32 m0, s22, 0x10000
	ds_read_b128 v[194:197], v189 offset:16384
	ds_read_b128 v[198:201], v189 offset:17408
	ds_read_b128 v[202:205], v189 offset:18432
	global_load_lds_dwordx4 v134, s[12:13]
	s_add_i32 m0, s22, 0x12000
	ds_read_b128 v[206:209], v189 offset:19456
	global_load_lds_dwordx4 v130, s[12:13]
	s_barrier
	s_waitcnt lgkmcnt(0)
	v_mfma_f32_16x16x32_bf16 v[118:121], v[194:197], v[160:163], 0
	v_mfma_f32_16x16x32_bf16 v[114:117], v[202:205], v[160:163], 0
	v_mfma_f32_16x16x32_bf16 v[102:105], v[194:197], v[168:171], 0
	v_mfma_f32_16x16x32_bf16 v[98:101], v[202:205], v[168:171], 0
	v_mfma_f32_16x16x32_bf16 v[86:89], v[194:197], v[176:179], 0
	v_mfma_f32_16x16x32_bf16 v[82:85], v[202:205], v[176:179], 0
	v_mfma_f32_16x16x32_bf16 v[70:73], v[194:197], v[184:187], 0
	v_mfma_f32_16x16x32_bf16 v[66:69], v[202:205], v[184:187], 0
	v_mfma_f32_16x16x32_bf16 v[118:121], v[198:201], v[164:167], v[118:121]
	v_mfma_f32_16x16x32_bf16 v[114:117], v[206:209], v[164:167], v[114:117]
	v_mfma_f32_16x16x32_bf16 v[102:105], v[198:201], v[172:175], v[102:105]
	v_mfma_f32_16x16x32_bf16 v[98:101], v[206:209], v[172:175], v[98:101]
	v_mfma_f32_16x16x32_bf16 v[86:89], v[198:201], v[180:183], v[86:89]
	v_mfma_f32_16x16x32_bf16 v[82:85], v[206:209], v[180:183], v[82:85]
	v_mfma_f32_16x16x32_bf16 v[70:73], v[198:201], v[190:193], v[70:73]
	v_mfma_f32_16x16x32_bf16 v[66:69], v[206:209], v[190:193], v[66:69]
	s_mov_b32 m0, s7
	s_mov_b64 s[100:101], s[14:15]
	s_barrier
	ds_read_b128 v[160:163], v151 offset:16384
	ds_read_b128 v[164:167], v151 offset:17408
	ds_read_b128 v[168:171], v151 offset:18432
	ds_read_b128 v[172:175], v151 offset:19456
	ds_read_b128 v[176:179], v151 offset:20480
	ds_read_b128 v[180:183], v151 offset:21504
	ds_read_b128 v[184:187], v151 offset:22528
	global_load_lds_dwordx4 v136, s[100:101]
	s_mov_b32 m0, s23
	ds_read_b128 v[190:193], v151 offset:23552
	global_load_lds_dwordx4 v132, s[100:101]
	s_waitcnt vmcnt(10)
	s_barrier
	s_waitcnt lgkmcnt(0)
	v_mfma_f32_16x16x32_bf16 v[62:65], v[142:145], v[160:163], 0
	v_mfma_f32_16x16x32_bf16 v[58:61], v[152:155], v[160:163], 0
	v_mfma_f32_16x16x32_bf16 v[46:49], v[142:145], v[168:171], 0
	v_mfma_f32_16x16x32_bf16 v[42:45], v[152:155], v[168:171], 0
	v_mfma_f32_16x16x32_bf16 v[30:33], v[142:145], v[176:179], 0
	v_mfma_f32_16x16x32_bf16 v[26:29], v[152:155], v[176:179], 0
	v_mfma_f32_16x16x32_bf16 v[14:17], v[142:145], v[184:187], 0
	v_mfma_f32_16x16x32_bf16 v[10:13], v[152:155], v[184:187], 0
	v_mfma_f32_16x16x32_bf16 v[62:65], v[146:149], v[164:167], v[62:65]
	v_mfma_f32_16x16x32_bf16 v[58:61], v[156:159], v[164:167], v[58:61]
	v_mfma_f32_16x16x32_bf16 v[46:49], v[146:149], v[172:175], v[46:49]
	v_mfma_f32_16x16x32_bf16 v[42:45], v[156:159], v[172:175], v[42:45]
	v_mfma_f32_16x16x32_bf16 v[30:33], v[146:149], v[180:183], v[30:33]
	v_mfma_f32_16x16x32_bf16 v[26:29], v[156:159], v[180:183], v[26:29]
	v_mfma_f32_16x16x32_bf16 v[14:17], v[146:149], v[190:193], v[14:17]
	v_mfma_f32_16x16x32_bf16 v[10:13], v[156:159], v[190:193], v[10:13]
	s_barrier
	s_add_u32 s86, s12, 0x40000
	s_addc_u32 s87, s13, 0
	s_add_i32 m0, s22, 0x14000
	s_nop 0
	global_load_lds_dwordx4 v134, s[86:87]
	s_add_i32 m0, s22, 0x16000
	s_nop 0
	global_load_lds_dwordx4 v130, s[86:87]
	ds_read_b128 v[142:145], v189 offset:32768
	ds_read_b128 v[146:149], v189 offset:33792
	ds_read_b128 v[152:155], v189 offset:34816
	ds_read_b128 v[156:159], v189 offset:35840
	s_waitcnt vmcnt(6)
	s_barrier
	v_mfma_f32_16x16x32_bf16 v[54:57], v[194:197], v[160:163], 0
	v_mfma_f32_16x16x32_bf16 v[50:53], v[202:205], v[160:163], 0
	v_mfma_f32_16x16x32_bf16 v[38:41], v[194:197], v[168:171], 0
	v_mfma_f32_16x16x32_bf16 v[34:37], v[202:205], v[168:171], 0
	v_mfma_f32_16x16x32_bf16 v[22:25], v[194:197], v[176:179], 0
	v_mfma_f32_16x16x32_bf16 v[18:21], v[202:205], v[176:179], 0
	v_mfma_f32_16x16x32_bf16 v[6:9], v[194:197], v[184:187], 0
	v_mfma_f32_16x16x32_bf16 v[2:5], v[202:205], v[184:187], 0
	v_mfma_f32_16x16x32_bf16 v[54:57], v[198:201], v[164:167], v[54:57]
	v_mfma_f32_16x16x32_bf16 v[50:53], v[206:209], v[164:167], v[50:53]
	v_mfma_f32_16x16x32_bf16 v[38:41], v[198:201], v[172:175], v[38:41]
	v_mfma_f32_16x16x32_bf16 v[34:37], v[206:209], v[172:175], v[34:37]
	v_mfma_f32_16x16x32_bf16 v[22:25], v[198:201], v[180:183], v[22:25]
	v_mfma_f32_16x16x32_bf16 v[18:21], v[206:209], v[180:183], v[18:21]
	v_mfma_f32_16x16x32_bf16 v[6:9], v[198:201], v[190:193], v[6:9]
	v_mfma_f32_16x16x32_bf16 v[2:5], v[206:209], v[190:193], v[2:5]
	s_barrier
	s_add_u32 s14, s14, 0x40000
	s_addc_u32 s15, s15, 0
	s_mov_b32 m0, s28
	ds_read_b128 v[160:163], v151 offset:32768
	ds_read_b128 v[164:167], v151 offset:33792
	ds_read_b128 v[168:171], v151 offset:34816
	ds_read_b128 v[172:175], v151 offset:35840
	ds_read_b128 v[176:179], v151 offset:36864
	ds_read_b128 v[180:183], v151 offset:37888
	ds_read_b128 v[184:187], v151 offset:38912
	global_load_lds_dwordx4 v136, s[14:15]
	s_mov_b32 m0, s29
	ds_read_b128 v[190:193], v151 offset:39936
	global_load_lds_dwordx4 v132, s[14:15]
	s_waitcnt lgkmcnt(8)
	s_barrier
	s_waitcnt lgkmcnt(0)
	v_mfma_f32_16x16x32_bf16 v[126:129], v[142:145], v[160:163], v[126:129]
	v_mfma_f32_16x16x32_bf16 v[122:125], v[152:155], v[160:163], v[122:125]
	v_mfma_f32_16x16x32_bf16 v[110:113], v[142:145], v[168:171], v[110:113]
	v_mfma_f32_16x16x32_bf16 v[106:109], v[152:155], v[168:171], v[106:109]
	v_mfma_f32_16x16x32_bf16 v[94:97], v[142:145], v[176:179], v[94:97]
	v_mfma_f32_16x16x32_bf16 v[90:93], v[152:155], v[176:179], v[90:93]
	v_mfma_f32_16x16x32_bf16 v[78:81], v[142:145], v[184:187], v[78:81]
	v_mfma_f32_16x16x32_bf16 v[74:77], v[152:155], v[184:187], v[74:77]
	v_mfma_f32_16x16x32_bf16 v[126:129], v[146:149], v[164:167], v[126:129]
	v_mfma_f32_16x16x32_bf16 v[122:125], v[156:159], v[164:167], v[122:125]
	v_mfma_f32_16x16x32_bf16 v[110:113], v[146:149], v[172:175], v[110:113]
	v_mfma_f32_16x16x32_bf16 v[106:109], v[156:159], v[172:175], v[106:109]
	v_mfma_f32_16x16x32_bf16 v[94:97], v[146:149], v[180:183], v[94:97]
	v_mfma_f32_16x16x32_bf16 v[90:93], v[156:159], v[180:183], v[90:93]
	v_mfma_f32_16x16x32_bf16 v[78:81], v[146:149], v[190:193], v[78:81]
	v_mfma_f32_16x16x32_bf16 v[74:77], v[156:159], v[190:193], v[74:77]
	s_barrier
	s_add_i32 m0, s22, 0x18000
	ds_read_b128 v[194:197], v189 offset:49152
	ds_read_b128 v[198:201], v189 offset:50176
	ds_read_b128 v[202:205], v189 offset:51200
	ds_read_b128 v[206:209], v189 offset:52224
	s_add_u32 s98, s12, s40
	s_addc_u32 s99, s13, s41
	global_load_lds_dwordx4 v134, s[98:99]
	s_add_i32 m0, s22, 0x1a000
	s_nop 0
	global_load_lds_dwordx4 v130, s[98:99]
	s_barrier
	s_waitcnt lgkmcnt(0)
	v_mfma_f32_16x16x32_bf16 v[118:121], v[194:197], v[160:163], v[118:121]
	v_mfma_f32_16x16x32_bf16 v[114:117], v[202:205], v[160:163], v[114:117]
	v_mfma_f32_16x16x32_bf16 v[102:105], v[194:197], v[168:171], v[102:105]
	v_mfma_f32_16x16x32_bf16 v[98:101], v[202:205], v[168:171], v[98:101]
	v_mfma_f32_16x16x32_bf16 v[86:89], v[194:197], v[176:179], v[86:89]
	v_mfma_f32_16x16x32_bf16 v[82:85], v[202:205], v[176:179], v[82:85]
	v_mfma_f32_16x16x32_bf16 v[70:73], v[194:197], v[184:187], v[70:73]
	v_mfma_f32_16x16x32_bf16 v[66:69], v[202:205], v[184:187], v[66:69]
	v_mfma_f32_16x16x32_bf16 v[118:121], v[198:201], v[164:167], v[118:121]
	v_mfma_f32_16x16x32_bf16 v[114:117], v[206:209], v[164:167], v[114:117]
	v_mfma_f32_16x16x32_bf16 v[102:105], v[198:201], v[172:175], v[102:105]
	v_mfma_f32_16x16x32_bf16 v[98:101], v[206:209], v[172:175], v[98:101]
	v_mfma_f32_16x16x32_bf16 v[86:89], v[198:201], v[180:183], v[86:89]
	v_mfma_f32_16x16x32_bf16 v[82:85], v[206:209], v[180:183], v[82:85]
	v_mfma_f32_16x16x32_bf16 v[70:73], v[198:201], v[190:193], v[70:73]
	v_mfma_f32_16x16x32_bf16 v[66:69], v[206:209], v[190:193], v[66:69]
	s_mov_b32 m0, s38
	s_barrier
	ds_read_b128 v[160:163], v151 offset:49152
	ds_read_b128 v[164:167], v151 offset:50176
	ds_read_b128 v[168:171], v151 offset:51200
	ds_read_b128 v[172:175], v151 offset:52224
	ds_read_b128 v[176:179], v151 offset:53248
	ds_read_b128 v[180:183], v151 offset:54272
	ds_read_b128 v[184:187], v151 offset:55296
	ds_read_b128 v[190:193], v151 offset:56320
	s_add_u32 s98, s100, s40
	s_addc_u32 s99, s101, s41
	global_load_lds_dwordx4 v136, s[98:99]
	s_mov_b32 m0, s39
	s_nop 0
	global_load_lds_dwordx4 v132, s[98:99]
	s_waitcnt vmcnt(10)
	s_barrier
	s_waitcnt lgkmcnt(0)
	v_mfma_f32_16x16x32_bf16 v[62:65], v[142:145], v[160:163], v[62:65]
	v_mfma_f32_16x16x32_bf16 v[58:61], v[152:155], v[160:163], v[58:61]
	v_mfma_f32_16x16x32_bf16 v[46:49], v[142:145], v[168:171], v[46:49]
	v_mfma_f32_16x16x32_bf16 v[42:45], v[152:155], v[168:171], v[42:45]
	v_mfma_f32_16x16x32_bf16 v[30:33], v[142:145], v[176:179], v[30:33]
	v_mfma_f32_16x16x32_bf16 v[26:29], v[152:155], v[176:179], v[26:29]
	v_mfma_f32_16x16x32_bf16 v[14:17], v[142:145], v[184:187], v[14:17]
	v_mfma_f32_16x16x32_bf16 v[10:13], v[152:155], v[184:187], v[10:13]
	v_mfma_f32_16x16x32_bf16 v[62:65], v[146:149], v[164:167], v[62:65]
	v_mfma_f32_16x16x32_bf16 v[58:61], v[156:159], v[164:167], v[58:61]
	v_mfma_f32_16x16x32_bf16 v[46:49], v[146:149], v[172:175], v[46:49]
	v_mfma_f32_16x16x32_bf16 v[42:45], v[156:159], v[172:175], v[42:45]
	v_mfma_f32_16x16x32_bf16 v[30:33], v[146:149], v[180:183], v[30:33]
	v_mfma_f32_16x16x32_bf16 v[26:29], v[156:159], v[180:183], v[26:29]
	v_mfma_f32_16x16x32_bf16 v[14:17], v[146:149], v[190:193], v[14:17]
	v_mfma_f32_16x16x32_bf16 v[10:13], v[156:159], v[190:193], v[10:13]
	s_barrier
	s_add_u32 s12, s12, 0x40080
	s_addc_u32 s13, s13, 0
	s_add_i32 m0, s22, 0x1c000
	s_nop 0
	global_load_lds_dwordx4 v134, s[12:13]
	s_add_i32 m0, s22, 0x1e000
	s_nop 0
	global_load_lds_dwordx4 v130, s[12:13]
	ds_read_b128 v[142:145], v189
	ds_read_b128 v[146:149], v189 offset:1024
	ds_read_b128 v[152:155], v189 offset:2048
	ds_read_b128 v[156:159], v189 offset:3072
	s_waitcnt vmcnt(6)
	s_barrier
	v_mfma_f32_16x16x32_bf16 v[54:57], v[194:197], v[160:163], v[54:57]
	v_mfma_f32_16x16x32_bf16 v[50:53], v[202:205], v[160:163], v[50:53]
	v_mfma_f32_16x16x32_bf16 v[38:41], v[194:197], v[168:171], v[38:41]
	v_mfma_f32_16x16x32_bf16 v[34:37], v[202:205], v[168:171], v[34:37]
	v_mfma_f32_16x16x32_bf16 v[22:25], v[194:197], v[176:179], v[22:25]
	v_mfma_f32_16x16x32_bf16 v[18:21], v[202:205], v[176:179], v[18:21]
	v_mfma_f32_16x16x32_bf16 v[6:9], v[194:197], v[184:187], v[6:9]
	v_mfma_f32_16x16x32_bf16 v[2:5], v[202:205], v[184:187], v[2:5]
	v_mfma_f32_16x16x32_bf16 v[54:57], v[198:201], v[164:167], v[54:57]
	v_mfma_f32_16x16x32_bf16 v[50:53], v[206:209], v[164:167], v[50:53]
	v_mfma_f32_16x16x32_bf16 v[38:41], v[198:201], v[172:175], v[38:41]
	v_mfma_f32_16x16x32_bf16 v[34:37], v[206:209], v[172:175], v[34:37]
	v_mfma_f32_16x16x32_bf16 v[22:25], v[198:201], v[180:183], v[22:25]
	v_mfma_f32_16x16x32_bf16 v[18:21], v[206:209], v[180:183], v[18:21]
	v_mfma_f32_16x16x32_bf16 v[6:9], v[198:201], v[190:193], v[6:9]
	v_mfma_f32_16x16x32_bf16 v[2:5], v[206:209], v[190:193], v[2:5]
	s_add_i32 s85, s85, 2
	s_add_u32 s4, s4, 0x100
	s_addc_u32 s5, s5, 0
	s_add_u32 s78, s78, 0x100
	s_addc_u32 s79, s79, 0
	s_add_u32 s12, s4, 0xfffc0080
	s_addc_u32 s13, s5, -1
	s_cmp_eq_u32 s85, 12
	s_cselect_b32 s15, s44, s13
	s_cselect_b32 s14, s45, s12
	s_cselect_b32 s13, s47, s79
	s_cselect_b32 s12, s55, s78
	s_cmp_gt_u32 s85, 13
	.p2align 3

.LBB0_837:
	s_ashr_i32 s15, s14, 31
	s_lshl_b64 s[78:79], s[14:15], 19
	s_add_u32 s84, s36, s78
	s_addc_u32 s85, s37, s79
	s_and_b64 s[4:5], s[4:5], exec
	s_cselect_b32 s15, s85, s91
	s_cselect_b32 s23, s84, s90
	s_add_u32 s34, s90, 0x100
	s_addc_u32 s75, s91, 0
	s_mov_b32 s78, -2
	s_waitcnt lgkmcnt(0)
	s_add_i32 s79, 0, 0x10000
	v_add_u32_e32 v142, s79, v212
	v_add_u32_e32 v189, 0x10000, v212
	ds_read_b128 v[130:133], v142
	ds_read_b128 v[134:137], v142 offset:1024
	ds_read_b128 v[138:141], v142 offset:2048
	ds_read_b128 v[142:145], v142 offset:3072
	s_add_u32 s4, s88, 0x100
	s_addc_u32 s5, s89, 0
	s_cmp_eq_u32 s78, 12
	s_cselect_b32 s93, s17, s5
	s_cselect_b32 s92, s16, s4
	s_cselect_b32 s91, s15, s75
	s_cselect_b32 s90, s23, s34
	v_lshl_add_u64 v[178:179], s[88:89], 0, v[196:197]
	s_add_i32 m0, s39, 0xc000
	ds_read_b128 v[146:149], v213
	ds_read_b128 v[150:153], v213 offset:1024
	ds_read_b128 v[154:157], v213 offset:2048
	ds_read_b128 v[158:161], v213 offset:3072
	ds_read_b128 v[162:165], v213 offset:4096
	ds_read_b128 v[166:169], v213 offset:5120
	ds_read_b128 v[170:173], v213 offset:6144
	ds_read_b128 v[174:177], v213 offset:7168
	global_load_lds_dwordx4 v[178:179], off
	s_add_i32 m0, s39, 0xe000
	v_lshl_add_u64 v[178:179], s[88:89], 0, v[198:199]
	global_load_lds_dwordx4 v[178:179], off
	s_waitcnt lgkmcnt(8)
	s_barrier
	s_waitcnt lgkmcnt(0)
	v_mfma_f32_16x16x32_bf16 v[126:129], v[130:133], v[146:149], 0
	v_mfma_f32_16x16x32_bf16 v[122:125], v[138:141], v[146:149], 0
	v_mfma_f32_16x16x32_bf16 v[110:113], v[130:133], v[154:157], 0
	v_mfma_f32_16x16x32_bf16 v[106:109], v[138:141], v[154:157], 0
	v_mfma_f32_16x16x32_bf16 v[94:97], v[130:133], v[162:165], 0
	v_mfma_f32_16x16x32_bf16 v[90:93], v[138:141], v[162:165], 0
	v_mfma_f32_16x16x32_bf16 v[78:81], v[130:133], v[170:173], 0
	v_mfma_f32_16x16x32_bf16 v[74:77], v[138:141], v[170:173], 0
	v_mfma_f32_16x16x32_bf16 v[126:129], v[134:137], v[150:153], v[126:129]
	v_mfma_f32_16x16x32_bf16 v[122:125], v[142:145], v[150:153], v[122:125]
	v_mfma_f32_16x16x32_bf16 v[110:113], v[134:137], v[158:161], v[110:113]
	v_mfma_f32_16x16x32_bf16 v[106:109], v[142:145], v[158:161], v[106:109]
	v_mfma_f32_16x16x32_bf16 v[94:97], v[134:137], v[166:169], v[94:97]
	v_mfma_f32_16x16x32_bf16 v[90:93], v[142:145], v[166:169], v[90:93]
	v_mfma_f32_16x16x32_bf16 v[78:81], v[134:137], v[174:177], v[78:81]
	v_mfma_f32_16x16x32_bf16 v[74:77], v[142:145], v[174:177], v[74:77]
	s_barrier
	ds_read_b128 v[178:181], v189 offset:16384
	ds_read_b128 v[182:185], v189 offset:17408
	ds_read_b128 v[200:203], v189 offset:18432
	ds_read_b128 v[204:207], v189 offset:19456
	s_add_i32 m0, s38, 0x10000
	s_nop 0
	global_load_lds_dwordx4 v0, s[90:91]
	s_add_i32 m0, s38, 0x12000
	s_nop 0
	global_load_lds_dwordx4 v194, s[90:91]
	s_barrier
	s_waitcnt lgkmcnt(0)
	v_mfma_f32_16x16x32_bf16 v[118:121], v[178:181], v[146:149], 0
	v_mfma_f32_16x16x32_bf16 v[114:117], v[200:203], v[146:149], 0
	v_mfma_f32_16x16x32_bf16 v[102:105], v[178:181], v[154:157], 0
	v_mfma_f32_16x16x32_bf16 v[98:101], v[200:203], v[154:157], 0
	v_mfma_f32_16x16x32_bf16 v[86:89], v[178:181], v[162:165], 0
	v_mfma_f32_16x16x32_bf16 v[82:85], v[200:203], v[162:165], 0
	v_mfma_f32_16x16x32_bf16 v[70:73], v[178:181], v[170:173], 0
	v_mfma_f32_16x16x32_bf16 v[66:69], v[200:203], v[170:173], 0
	v_mfma_f32_16x16x32_bf16 v[118:121], v[182:185], v[150:153], v[118:121]
	v_mfma_f32_16x16x32_bf16 v[114:117], v[204:207], v[150:153], v[114:117]
	v_mfma_f32_16x16x32_bf16 v[102:105], v[182:185], v[158:161], v[102:105]
	v_mfma_f32_16x16x32_bf16 v[98:101], v[204:207], v[158:161], v[98:101]
	v_mfma_f32_16x16x32_bf16 v[86:89], v[182:185], v[166:169], v[86:89]
	v_mfma_f32_16x16x32_bf16 v[82:85], v[204:207], v[166:169], v[82:85]
	v_mfma_f32_16x16x32_bf16 v[70:73], v[182:185], v[174:177], v[70:73]
	v_mfma_f32_16x16x32_bf16 v[66:69], v[204:207], v[174:177], v[66:69]
	s_mov_b32 m0, s39
	s_barrier
	ds_read_b128 v[146:149], v213 offset:16384
	ds_read_b128 v[150:153], v213 offset:17408
	ds_read_b128 v[154:157], v213 offset:18432
	ds_read_b128 v[158:161], v213 offset:19456
	ds_read_b128 v[162:165], v213 offset:20480
	ds_read_b128 v[166:169], v213 offset:21504
	ds_read_b128 v[170:173], v213 offset:22528
	global_load_lds_dwordx4 v190, s[92:93]
	s_mov_b32 m0, s42
	ds_read_b128 v[174:177], v213 offset:23552
	global_load_lds_dwordx4 v192, s[92:93]
	s_waitcnt vmcnt(10)
	s_barrier
	s_waitcnt lgkmcnt(0)
	v_mfma_f32_16x16x32_bf16 v[62:65], v[130:133], v[146:149], 0
	v_mfma_f32_16x16x32_bf16 v[58:61], v[138:141], v[146:149], 0
	v_mfma_f32_16x16x32_bf16 v[46:49], v[130:133], v[154:157], 0
	v_mfma_f32_16x16x32_bf16 v[42:45], v[138:141], v[154:157], 0
	v_mfma_f32_16x16x32_bf16 v[30:33], v[130:133], v[162:165], 0
	v_mfma_f32_16x16x32_bf16 v[26:29], v[138:141], v[162:165], 0
	v_mfma_f32_16x16x32_bf16 v[14:17], v[130:133], v[170:173], 0
	v_mfma_f32_16x16x32_bf16 v[10:13], v[138:141], v[170:173], 0
	v_mfma_f32_16x16x32_bf16 v[62:65], v[134:137], v[150:153], v[62:65]
	v_mfma_f32_16x16x32_bf16 v[58:61], v[142:145], v[150:153], v[58:61]
	v_mfma_f32_16x16x32_bf16 v[46:49], v[134:137], v[158:161], v[46:49]
	v_mfma_f32_16x16x32_bf16 v[42:45], v[142:145], v[158:161], v[42:45]
	v_mfma_f32_16x16x32_bf16 v[30:33], v[134:137], v[166:169], v[30:33]
	v_mfma_f32_16x16x32_bf16 v[26:29], v[142:145], v[166:169], v[26:29]
	v_mfma_f32_16x16x32_bf16 v[14:17], v[134:137], v[174:177], v[14:17]
	v_mfma_f32_16x16x32_bf16 v[10:13], v[142:145], v[174:177], v[10:13]
	s_barrier
	s_add_u32 s88, s90, 0x40000
	s_addc_u32 s89, s91, 0
	s_add_i32 m0, s38, 0x14000
	s_nop 0
	global_load_lds_dwordx4 v0, s[88:89]
	s_add_i32 m0, s38, 0x16000
	s_nop 0
	global_load_lds_dwordx4 v194, s[88:89]
	s_add_i32 s79, 0, 0x18000
	v_add_u32_e32 v142, s79, v212
	ds_read_b128 v[130:133], v142
	ds_read_b128 v[134:137], v142 offset:1024
	ds_read_b128 v[138:141], v142 offset:2048
	ds_read_b128 v[142:145], v142 offset:3072
	s_waitcnt vmcnt(6)
	s_barrier
	v_mfma_f32_16x16x32_bf16 v[54:57], v[178:181], v[146:149], 0
	v_mfma_f32_16x16x32_bf16 v[50:53], v[200:203], v[146:149], 0
	v_mfma_f32_16x16x32_bf16 v[38:41], v[178:181], v[154:157], 0
	v_mfma_f32_16x16x32_bf16 v[34:37], v[200:203], v[154:157], 0
	v_mfma_f32_16x16x32_bf16 v[22:25], v[178:181], v[162:165], 0
	v_mfma_f32_16x16x32_bf16 v[18:21], v[200:203], v[162:165], 0
	v_mfma_f32_16x16x32_bf16 v[6:9], v[178:181], v[170:173], 0
	v_mfma_f32_16x16x32_bf16 v[2:5], v[200:203], v[170:173], 0
	v_mfma_f32_16x16x32_bf16 v[54:57], v[182:185], v[150:153], v[54:57]
	v_mfma_f32_16x16x32_bf16 v[50:53], v[204:207], v[150:153], v[50:53]
	v_mfma_f32_16x16x32_bf16 v[38:41], v[182:185], v[158:161], v[38:41]
	v_mfma_f32_16x16x32_bf16 v[34:37], v[204:207], v[158:161], v[34:37]
	v_mfma_f32_16x16x32_bf16 v[22:25], v[182:185], v[166:169], v[22:25]
	v_mfma_f32_16x16x32_bf16 v[18:21], v[204:207], v[166:169], v[18:21]
	v_mfma_f32_16x16x32_bf16 v[6:9], v[182:185], v[174:177], v[6:9]
	v_mfma_f32_16x16x32_bf16 v[2:5], v[204:207], v[174:177], v[2:5]
	s_barrier
	s_add_u32 s88, s92, 0xc0000
	s_addc_u32 s89, s93, 0
	s_mov_b32 m0, s43
	ds_read_b128 v[146:149], v213 offset:32768
	ds_read_b128 v[150:153], v213 offset:33792
	ds_read_b128 v[154:157], v213 offset:34816
	ds_read_b128 v[158:161], v213 offset:35840
	ds_read_b128 v[162:165], v213 offset:36864
	ds_read_b128 v[166:169], v213 offset:37888
	ds_read_b128 v[170:173], v213 offset:38912
	global_load_lds_dwordx4 v190, s[88:89]
	s_mov_b32 m0, s44
	ds_read_b128 v[174:177], v213 offset:39936
	global_load_lds_dwordx4 v192, s[88:89]
	s_waitcnt lgkmcnt(8)
	s_barrier
	s_waitcnt lgkmcnt(0)
	v_mfma_f32_16x16x32_bf16 v[126:129], v[130:133], v[146:149], v[126:129]
	v_mfma_f32_16x16x32_bf16 v[122:125], v[138:141], v[146:149], v[122:125]
	v_mfma_f32_16x16x32_bf16 v[110:113], v[130:133], v[154:157], v[110:113]
	v_mfma_f32_16x16x32_bf16 v[106:109], v[138:141], v[154:157], v[106:109]
	v_mfma_f32_16x16x32_bf16 v[94:97], v[130:133], v[162:165], v[94:97]
	v_mfma_f32_16x16x32_bf16 v[90:93], v[138:141], v[162:165], v[90:93]
	v_mfma_f32_16x16x32_bf16 v[78:81], v[130:133], v[170:173], v[78:81]
	v_mfma_f32_16x16x32_bf16 v[74:77], v[138:141], v[170:173], v[74:77]
	v_mfma_f32_16x16x32_bf16 v[126:129], v[134:137], v[150:153], v[126:129]
	v_mfma_f32_16x16x32_bf16 v[122:125], v[142:145], v[150:153], v[122:125]
	v_mfma_f32_16x16x32_bf16 v[110:113], v[134:137], v[158:161], v[110:113]
	v_mfma_f32_16x16x32_bf16 v[106:109], v[142:145], v[158:161], v[106:109]
	v_mfma_f32_16x16x32_bf16 v[94:97], v[134:137], v[166:169], v[94:97]
	v_mfma_f32_16x16x32_bf16 v[90:93], v[142:145], v[166:169], v[90:93]
	v_mfma_f32_16x16x32_bf16 v[78:81], v[134:137], v[174:177], v[78:81]
	v_mfma_f32_16x16x32_bf16 v[74:77], v[142:145], v[174:177], v[74:77]
	s_barrier
	s_add_i32 s87, 0, 0x1c000
	v_add_u32_e32 v204, s87, v212
	s_add_i32 m0, s38, 0x18000
	ds_read_b128 v[178:181], v204
	ds_read_b128 v[182:185], v204 offset:1024
	ds_read_b128 v[200:203], v204 offset:2048
	ds_read_b128 v[204:207], v204 offset:3072
	s_add_u32 s98, s90, s40
	s_addc_u32 s99, s91, s41
	global_load_lds_dwordx4 v0, s[98:99]
	s_add_i32 m0, s38, 0x1a000
	s_nop 0
	global_load_lds_dwordx4 v194, s[98:99]
	s_barrier
	s_waitcnt lgkmcnt(0)
	v_mfma_f32_16x16x32_bf16 v[118:121], v[178:181], v[146:149], v[118:121]
	v_mfma_f32_16x16x32_bf16 v[114:117], v[200:203], v[146:149], v[114:117]
	v_mfma_f32_16x16x32_bf16 v[102:105], v[178:181], v[154:157], v[102:105]
	v_mfma_f32_16x16x32_bf16 v[98:101], v[200:203], v[154:157], v[98:101]
	v_mfma_f32_16x16x32_bf16 v[86:89], v[178:181], v[162:165], v[86:89]
	v_mfma_f32_16x16x32_bf16 v[82:85], v[200:203], v[162:165], v[82:85]
	v_mfma_f32_16x16x32_bf16 v[70:73], v[178:181], v[170:173], v[70:73]
	v_mfma_f32_16x16x32_bf16 v[66:69], v[200:203], v[170:173], v[66:69]
	v_mfma_f32_16x16x32_bf16 v[118:121], v[182:185], v[150:153], v[118:121]
	v_mfma_f32_16x16x32_bf16 v[114:117], v[204:207], v[150:153], v[114:117]
	v_mfma_f32_16x16x32_bf16 v[102:105], v[182:185], v[158:161], v[102:105]
	v_mfma_f32_16x16x32_bf16 v[98:101], v[204:207], v[158:161], v[98:101]
	v_mfma_f32_16x16x32_bf16 v[86:89], v[182:185], v[166:169], v[86:89]
	v_mfma_f32_16x16x32_bf16 v[82:85], v[204:207], v[166:169], v[82:85]
	v_mfma_f32_16x16x32_bf16 v[70:73], v[182:185], v[174:177], v[70:73]
	v_mfma_f32_16x16x32_bf16 v[66:69], v[204:207], v[174:177], v[66:69]
	s_mov_b32 m0, s60
	s_barrier
	ds_read_b128 v[146:149], v213 offset:49152
	ds_read_b128 v[150:153], v213 offset:50176
	ds_read_b128 v[154:157], v213 offset:51200
	ds_read_b128 v[158:161], v213 offset:52224
	ds_read_b128 v[162:165], v213 offset:53248
	ds_read_b128 v[166:169], v213 offset:54272
	ds_read_b128 v[170:173], v213 offset:55296
	ds_read_b128 v[174:177], v213 offset:56320
	s_add_u32 s98, s92, s40
	s_addc_u32 s99, s93, s41
	global_load_lds_dwordx4 v190, s[98:99]
	s_mov_b32 m0, s61
	s_nop 0
	global_load_lds_dwordx4 v192, s[98:99]
	s_waitcnt vmcnt(10)
	s_barrier
	s_waitcnt lgkmcnt(0)
	v_mfma_f32_16x16x32_bf16 v[62:65], v[130:133], v[146:149], v[62:65]
	v_mfma_f32_16x16x32_bf16 v[58:61], v[138:141], v[146:149], v[58:61]
	v_mfma_f32_16x16x32_bf16 v[46:49], v[130:133], v[154:157], v[46:49]
	v_mfma_f32_16x16x32_bf16 v[42:45], v[138:141], v[154:157], v[42:45]
	v_mfma_f32_16x16x32_bf16 v[30:33], v[130:133], v[162:165], v[30:33]
	v_mfma_f32_16x16x32_bf16 v[26:29], v[138:141], v[162:165], v[26:29]
	v_mfma_f32_16x16x32_bf16 v[14:17], v[130:133], v[170:173], v[14:17]
	v_mfma_f32_16x16x32_bf16 v[10:13], v[138:141], v[170:173], v[10:13]
	v_mfma_f32_16x16x32_bf16 v[62:65], v[134:137], v[150:153], v[62:65]
	v_mfma_f32_16x16x32_bf16 v[58:61], v[142:145], v[150:153], v[58:61]
	v_mfma_f32_16x16x32_bf16 v[46:49], v[134:137], v[158:161], v[46:49]
	v_mfma_f32_16x16x32_bf16 v[42:45], v[142:145], v[158:161], v[42:45]
	v_mfma_f32_16x16x32_bf16 v[30:33], v[134:137], v[166:169], v[30:33]
	v_mfma_f32_16x16x32_bf16 v[26:29], v[142:145], v[166:169], v[26:29]
	v_mfma_f32_16x16x32_bf16 v[14:17], v[134:137], v[174:177], v[14:17]
	v_mfma_f32_16x16x32_bf16 v[10:13], v[142:145], v[174:177], v[10:13]
	s_barrier
	s_add_u32 s88, s90, 0x40080
	s_addc_u32 s89, s91, 0
	s_add_i32 m0, s38, 0x1c000
	s_nop 0
	global_load_lds_dwordx4 v0, s[88:89]
	s_add_i32 m0, s38, 0x1e000
	s_nop 0
	global_load_lds_dwordx4 v194, s[88:89]
	ds_read_b128 v[130:133], v189
	ds_read_b128 v[134:137], v189 offset:1024
	ds_read_b128 v[138:141], v189 offset:2048
	ds_read_b128 v[142:145], v189 offset:3072
	s_waitcnt vmcnt(6)
	s_barrier
	v_mfma_f32_16x16x32_bf16 v[54:57], v[178:181], v[146:149], v[54:57]
	v_mfma_f32_16x16x32_bf16 v[50:53], v[200:203], v[146:149], v[50:53]
	v_mfma_f32_16x16x32_bf16 v[38:41], v[178:181], v[154:157], v[38:41]
	v_mfma_f32_16x16x32_bf16 v[34:37], v[200:203], v[154:157], v[34:37]
	v_mfma_f32_16x16x32_bf16 v[22:25], v[178:181], v[162:165], v[22:25]
	v_mfma_f32_16x16x32_bf16 v[18:21], v[200:203], v[162:165], v[18:21]
	v_mfma_f32_16x16x32_bf16 v[6:9], v[178:181], v[170:173], v[6:9]
	v_mfma_f32_16x16x32_bf16 v[2:5], v[200:203], v[170:173], v[2:5]
	v_mfma_f32_16x16x32_bf16 v[54:57], v[182:185], v[150:153], v[54:57]
	v_mfma_f32_16x16x32_bf16 v[50:53], v[204:207], v[150:153], v[50:53]
	v_mfma_f32_16x16x32_bf16 v[38:41], v[182:185], v[158:161], v[38:41]
	v_mfma_f32_16x16x32_bf16 v[34:37], v[204:207], v[158:161], v[34:37]
	v_mfma_f32_16x16x32_bf16 v[22:25], v[182:185], v[166:169], v[22:25]
	v_mfma_f32_16x16x32_bf16 v[18:21], v[204:207], v[166:169], v[18:21]
	v_mfma_f32_16x16x32_bf16 v[6:9], v[182:185], v[174:177], v[6:9]
	v_mfma_f32_16x16x32_bf16 v[2:5], v[204:207], v[174:177], v[2:5]
	s_add_i32 s78, s78, 2
	s_add_u32 s34, s34, 0x100
	s_addc_u32 s75, s75, 0
	s_mov_b64 s[88:89], s[4:5]
	s_add_u32 s4, s88, 0x100
	s_addc_u32 s5, s89, 0
	s_cmp_eq_u32 s78, 12
	s_cselect_b32 s93, s17, s5
	s_cselect_b32 s92, s16, s4
	s_cselect_b32 s91, s15, s75
	s_cselect_b32 s90, s23, s34
	s_cmp_gt_u32 s78, 13
	.p2align 3

.LBB0_918:
	s_ashr_i32 s17, s16, 31
	s_lshl_b64 s[22:23], s[16:17], 19
	v_mov_b64_e32 v[2:3], 0xb00
	s_add_u32 s84, s8, s22
	v_cmp_lt_i64_e32 vcc, s[28:29], v[2:3]
	s_addc_u32 s85, s9, s23
	s_and_b64 s[22:23], vcc, exec
	s_cselect_b32 s17, s85, s7
	s_cselect_b32 s22, s84, s6
	s_ashr_i32 s15, s14, 31
	s_lshl_b64 s[28:29], s[14:15], 19
	s_add_u32 s86, s37, s28
	s_addc_u32 s87, s38, s29
	s_and_b64 s[28:29], vcc, exec
	s_cselect_b32 s15, s87, s89
	s_cselect_b32 s23, s86, s88
	s_add_u32 s28, s88, 0x100
	s_addc_u32 s29, s89, 0
	s_mov_b32 s45, -2
	s_add_i32 vcc_lo, 0, 0x10000
	v_add_u32_e32 v0, vcc_lo, v254
	v_add_u32_e32 v189, 0x10000, v254
	ds_read_b128 v[130:133], v0
	ds_read_b128 v[134:137], v0 offset:1024
	ds_read_b128 v[138:141], v0 offset:2048
	ds_read_b128 v[142:145], v0 offset:3072
	s_add_u32 s88, s6, 0x100
	s_addc_u32 s89, s7, 0
	s_cmp_eq_u32 s45, 12
	s_cselect_b32 s93, s17, s89
	s_cselect_b32 s92, s22, s88
	s_cselect_b32 s91, s15, s29
	s_cselect_b32 s90, s23, s28
	s_add_i32 m0, s43, 0xc000
	ds_read_b128 v[146:149], v253
	ds_read_b128 v[150:153], v253 offset:1024
	ds_read_b128 v[168:171], v253 offset:2048
	ds_read_b128 v[172:175], v253 offset:3072
	ds_read_b128 v[176:179], v253 offset:4096
	ds_read_b128 v[180:183], v253 offset:5120
	ds_read_b128 v[184:187], v253 offset:6144
	ds_read_b128 v[190:193], v253 offset:7168
	global_load_lds_dwordx4 v164, s[6:7]
	s_add_i32 m0, s43, 0xe000
	v_lshl_add_u64 v[154:155], s[6:7], 0, v[166:167]
	global_load_lds_dwordx4 v[154:155], off
	s_waitcnt lgkmcnt(8)
	s_barrier
	s_waitcnt lgkmcnt(0)
	v_mfma_f32_16x16x32_bf16 v[126:129], v[130:133], v[146:149], 0
	v_mfma_f32_16x16x32_bf16 v[70:73], v[138:141], v[146:149], 0
	v_mfma_f32_16x16x32_bf16 v[122:125], v[130:133], v[168:171], 0
	v_mfma_f32_16x16x32_bf16 v[74:77], v[138:141], v[168:171], 0
	v_mfma_f32_16x16x32_bf16 v[114:117], v[130:133], v[176:179], 0
	v_mfma_f32_16x16x32_bf16 v[66:69], v[138:141], v[176:179], 0
	v_mfma_f32_16x16x32_bf16 v[110:113], v[130:133], v[184:187], 0
	v_mfma_f32_16x16x32_bf16 v[78:81], v[138:141], v[184:187], 0
	v_mfma_f32_16x16x32_bf16 v[126:129], v[134:137], v[150:153], v[126:129]
	v_mfma_f32_16x16x32_bf16 v[70:73], v[142:145], v[150:153], v[70:73]
	v_mfma_f32_16x16x32_bf16 v[122:125], v[134:137], v[172:175], v[122:125]
	v_mfma_f32_16x16x32_bf16 v[74:77], v[142:145], v[172:175], v[74:77]
	v_mfma_f32_16x16x32_bf16 v[114:117], v[134:137], v[180:183], v[114:117]
	v_mfma_f32_16x16x32_bf16 v[66:69], v[142:145], v[180:183], v[66:69]
	v_mfma_f32_16x16x32_bf16 v[110:113], v[134:137], v[190:193], v[110:113]
	v_mfma_f32_16x16x32_bf16 v[78:81], v[142:145], v[190:193], v[78:81]
	s_barrier
	s_add_i32 m0, s39, 0x10000
	ds_read_b128 v[194:197], v189 offset:16384
	ds_read_b128 v[198:201], v189 offset:17408
	ds_read_b128 v[202:205], v189 offset:18432
	global_load_lds_dwordx4 v160, s[90:91]
	s_add_i32 m0, s39, 0x12000
	ds_read_b128 v[206:209], v189 offset:19456
	global_load_lds_dwordx4 v156, s[90:91]
	s_barrier
	s_waitcnt lgkmcnt(0)
	v_mfma_f32_16x16x32_bf16 v[118:121], v[194:197], v[146:149], 0
	v_mfma_f32_16x16x32_bf16 v[94:97], v[202:205], v[146:149], 0
	v_mfma_f32_16x16x32_bf16 v[106:109], v[194:197], v[168:171], 0
	v_mfma_f32_16x16x32_bf16 v[90:93], v[202:205], v[168:171], 0
	v_mfma_f32_16x16x32_bf16 v[102:105], v[194:197], v[176:179], 0
	v_mfma_f32_16x16x32_bf16 v[82:85], v[202:205], v[176:179], 0
	v_mfma_f32_16x16x32_bf16 v[98:101], v[194:197], v[184:187], 0
	v_mfma_f32_16x16x32_bf16 v[86:89], v[202:205], v[184:187], 0
	v_mfma_f32_16x16x32_bf16 v[118:121], v[198:201], v[150:153], v[118:121]
	v_mfma_f32_16x16x32_bf16 v[94:97], v[206:209], v[150:153], v[94:97]
	v_mfma_f32_16x16x32_bf16 v[106:109], v[198:201], v[172:175], v[106:109]
	v_mfma_f32_16x16x32_bf16 v[90:93], v[206:209], v[172:175], v[90:93]
	v_mfma_f32_16x16x32_bf16 v[102:105], v[198:201], v[180:183], v[102:105]
	v_mfma_f32_16x16x32_bf16 v[82:85], v[206:209], v[180:183], v[82:85]
	v_mfma_f32_16x16x32_bf16 v[98:101], v[198:201], v[190:193], v[98:101]
	v_mfma_f32_16x16x32_bf16 v[86:89], v[206:209], v[190:193], v[86:89]
	s_mov_b32 m0, s43
	s_mov_b64 s[100:101], s[92:93]
	s_barrier
	ds_read_b128 v[146:149], v253 offset:16384
	ds_read_b128 v[150:153], v253 offset:17408
	ds_read_b128 v[168:171], v253 offset:18432
	ds_read_b128 v[172:175], v253 offset:19456
	ds_read_b128 v[176:179], v253 offset:20480
	ds_read_b128 v[180:183], v253 offset:21504
	ds_read_b128 v[184:187], v253 offset:22528
	global_load_lds_dwordx4 v162, s[100:101]
	s_mov_b32 m0, s60
	ds_read_b128 v[190:193], v253 offset:23552
	global_load_lds_dwordx4 v158, s[100:101]
	s_waitcnt vmcnt(10)
	s_barrier
	s_waitcnt lgkmcnt(0)
	v_mfma_f32_16x16x32_bf16 v[62:65], v[130:133], v[146:149], 0
	v_mfma_f32_16x16x32_bf16 v[10:13], v[138:141], v[146:149], 0
	v_mfma_f32_16x16x32_bf16 v[58:61], v[130:133], v[168:171], 0
	v_mfma_f32_16x16x32_bf16 v[14:17], v[138:141], v[168:171], 0
	v_mfma_f32_16x16x32_bf16 v[54:57], v[130:133], v[176:179], 0
	v_mfma_f32_16x16x32_bf16 v[6:9], v[138:141], v[176:179], 0
	v_mfma_f32_16x16x32_bf16 v[42:45], v[130:133], v[184:187], 0
	v_mfma_f32_16x16x32_bf16 v[2:5], v[138:141], v[184:187], 0
	v_mfma_f32_16x16x32_bf16 v[62:65], v[134:137], v[150:153], v[62:65]
	v_mfma_f32_16x16x32_bf16 v[10:13], v[142:145], v[150:153], v[10:13]
	v_mfma_f32_16x16x32_bf16 v[58:61], v[134:137], v[172:175], v[58:61]
	v_mfma_f32_16x16x32_bf16 v[14:17], v[142:145], v[172:175], v[14:17]
	v_mfma_f32_16x16x32_bf16 v[54:57], v[134:137], v[180:183], v[54:57]
	v_mfma_f32_16x16x32_bf16 v[6:9], v[142:145], v[180:183], v[6:9]
	v_mfma_f32_16x16x32_bf16 v[42:45], v[134:137], v[190:193], v[42:45]
	v_mfma_f32_16x16x32_bf16 v[2:5], v[142:145], v[190:193], v[2:5]
	s_barrier
	s_add_u32 s6, s90, 0x40000
	s_addc_u32 s7, s91, 0
	s_add_i32 m0, s39, 0x14000
	s_nop 0
	global_load_lds_dwordx4 v160, s[6:7]
	s_add_i32 m0, s39, 0x16000
	s_nop 0
	global_load_lds_dwordx4 v156, s[6:7]
	ds_read_b128 v[130:133], v189 offset:32768
	ds_read_b128 v[134:137], v189 offset:33792
	ds_read_b128 v[138:141], v189 offset:34816
	ds_read_b128 v[142:145], v189 offset:35840
	s_waitcnt vmcnt(6)
	s_barrier
	v_mfma_f32_16x16x32_bf16 v[50:53], v[194:197], v[146:149], 0
	v_mfma_f32_16x16x32_bf16 v[26:29], v[202:205], v[146:149], 0
	v_mfma_f32_16x16x32_bf16 v[46:49], v[194:197], v[168:171], 0
	v_mfma_f32_16x16x32_bf16 v[30:33], v[202:205], v[168:171], 0
	v_mfma_f32_16x16x32_bf16 v[38:41], v[194:197], v[176:179], 0
	v_mfma_f32_16x16x32_bf16 v[22:25], v[202:205], v[176:179], 0
	v_mfma_f32_16x16x32_bf16 v[34:37], v[194:197], v[184:187], 0
	v_mfma_f32_16x16x32_bf16 v[18:21], v[202:205], v[184:187], 0
	v_mfma_f32_16x16x32_bf16 v[50:53], v[198:201], v[150:153], v[50:53]
	v_mfma_f32_16x16x32_bf16 v[26:29], v[206:209], v[150:153], v[26:29]
	v_mfma_f32_16x16x32_bf16 v[46:49], v[198:201], v[172:175], v[46:49]
	v_mfma_f32_16x16x32_bf16 v[30:33], v[206:209], v[172:175], v[30:33]
	v_mfma_f32_16x16x32_bf16 v[38:41], v[198:201], v[180:183], v[38:41]
	v_mfma_f32_16x16x32_bf16 v[22:25], v[206:209], v[180:183], v[22:25]
	v_mfma_f32_16x16x32_bf16 v[34:37], v[198:201], v[190:193], v[34:37]
	v_mfma_f32_16x16x32_bf16 v[18:21], v[206:209], v[190:193], v[18:21]
	s_barrier
	s_add_u32 s6, s92, 0x40000
	s_addc_u32 s7, s93, 0
	s_mov_b32 m0, s61
	ds_read_b128 v[146:149], v253 offset:32768
	ds_read_b128 v[150:153], v253 offset:33792
	ds_read_b128 v[168:171], v253 offset:34816
	ds_read_b128 v[172:175], v253 offset:35840
	ds_read_b128 v[176:179], v253 offset:36864
	ds_read_b128 v[180:183], v253 offset:37888
	ds_read_b128 v[184:187], v253 offset:38912
	global_load_lds_dwordx4 v162, s[6:7]
	s_mov_b32 m0, s72
	ds_read_b128 v[190:193], v253 offset:39936
	global_load_lds_dwordx4 v158, s[6:7]
	s_waitcnt lgkmcnt(8)
	s_barrier
	s_waitcnt lgkmcnt(0)
	v_mfma_f32_16x16x32_bf16 v[126:129], v[130:133], v[146:149], v[126:129]
	v_mfma_f32_16x16x32_bf16 v[70:73], v[138:141], v[146:149], v[70:73]
	v_mfma_f32_16x16x32_bf16 v[122:125], v[130:133], v[168:171], v[122:125]
	v_mfma_f32_16x16x32_bf16 v[74:77], v[138:141], v[168:171], v[74:77]
	v_mfma_f32_16x16x32_bf16 v[114:117], v[130:133], v[176:179], v[114:117]
	v_mfma_f32_16x16x32_bf16 v[66:69], v[138:141], v[176:179], v[66:69]
	v_mfma_f32_16x16x32_bf16 v[110:113], v[130:133], v[184:187], v[110:113]
	v_mfma_f32_16x16x32_bf16 v[78:81], v[138:141], v[184:187], v[78:81]
	v_mfma_f32_16x16x32_bf16 v[126:129], v[134:137], v[150:153], v[126:129]
	v_mfma_f32_16x16x32_bf16 v[70:73], v[142:145], v[150:153], v[70:73]
	v_mfma_f32_16x16x32_bf16 v[122:125], v[134:137], v[172:175], v[122:125]
	v_mfma_f32_16x16x32_bf16 v[74:77], v[142:145], v[172:175], v[74:77]
	v_mfma_f32_16x16x32_bf16 v[114:117], v[134:137], v[180:183], v[114:117]
	v_mfma_f32_16x16x32_bf16 v[66:69], v[142:145], v[180:183], v[66:69]
	v_mfma_f32_16x16x32_bf16 v[110:113], v[134:137], v[190:193], v[110:113]
	v_mfma_f32_16x16x32_bf16 v[78:81], v[142:145], v[190:193], v[78:81]
	s_barrier
	s_add_i32 m0, s39, 0x18000
	ds_read_b128 v[194:197], v189 offset:49152
	ds_read_b128 v[198:201], v189 offset:50176
	ds_read_b128 v[202:205], v189 offset:51200
	ds_read_b128 v[206:209], v189 offset:52224
	s_add_u32 s98, s90, s40
	s_addc_u32 s99, s91, s41
	global_load_lds_dwordx4 v160, s[98:99]
	s_add_i32 m0, s39, 0x1a000
	s_nop 0
	global_load_lds_dwordx4 v156, s[98:99]
	s_barrier
	s_waitcnt lgkmcnt(0)
	v_mfma_f32_16x16x32_bf16 v[118:121], v[194:197], v[146:149], v[118:121]
	v_mfma_f32_16x16x32_bf16 v[94:97], v[202:205], v[146:149], v[94:97]
	v_mfma_f32_16x16x32_bf16 v[106:109], v[194:197], v[168:171], v[106:109]
	v_mfma_f32_16x16x32_bf16 v[90:93], v[202:205], v[168:171], v[90:93]
	v_mfma_f32_16x16x32_bf16 v[102:105], v[194:197], v[176:179], v[102:105]
	v_mfma_f32_16x16x32_bf16 v[82:85], v[202:205], v[176:179], v[82:85]
	v_mfma_f32_16x16x32_bf16 v[98:101], v[194:197], v[184:187], v[98:101]
	v_mfma_f32_16x16x32_bf16 v[86:89], v[202:205], v[184:187], v[86:89]
	v_mfma_f32_16x16x32_bf16 v[118:121], v[198:201], v[150:153], v[118:121]
	v_mfma_f32_16x16x32_bf16 v[94:97], v[206:209], v[150:153], v[94:97]
	v_mfma_f32_16x16x32_bf16 v[106:109], v[198:201], v[172:175], v[106:109]
	v_mfma_f32_16x16x32_bf16 v[90:93], v[206:209], v[172:175], v[90:93]
	v_mfma_f32_16x16x32_bf16 v[102:105], v[198:201], v[180:183], v[102:105]
	v_mfma_f32_16x16x32_bf16 v[82:85], v[206:209], v[180:183], v[82:85]
	v_mfma_f32_16x16x32_bf16 v[98:101], v[198:201], v[190:193], v[98:101]
	v_mfma_f32_16x16x32_bf16 v[86:89], v[206:209], v[190:193], v[86:89]
	s_mov_b32 m0, s95
	s_barrier
	ds_read_b128 v[146:149], v253 offset:49152
	ds_read_b128 v[150:153], v253 offset:50176
	ds_read_b128 v[168:171], v253 offset:51200
	ds_read_b128 v[172:175], v253 offset:52224
	ds_read_b128 v[176:179], v253 offset:53248
	ds_read_b128 v[180:183], v253 offset:54272
	ds_read_b128 v[184:187], v253 offset:55296
	ds_read_b128 v[190:193], v253 offset:56320
	s_add_u32 s98, s100, s40
	s_addc_u32 s99, s101, s41
	global_load_lds_dwordx4 v162, s[98:99]
	s_mov_b32 m0, s96
	s_nop 0
	global_load_lds_dwordx4 v158, s[98:99]
	s_waitcnt vmcnt(10)
	s_barrier
	s_waitcnt lgkmcnt(0)
	v_mfma_f32_16x16x32_bf16 v[62:65], v[130:133], v[146:149], v[62:65]
	v_mfma_f32_16x16x32_bf16 v[10:13], v[138:141], v[146:149], v[10:13]
	v_mfma_f32_16x16x32_bf16 v[58:61], v[130:133], v[168:171], v[58:61]
	v_mfma_f32_16x16x32_bf16 v[14:17], v[138:141], v[168:171], v[14:17]
	v_mfma_f32_16x16x32_bf16 v[54:57], v[130:133], v[176:179], v[54:57]
	v_mfma_f32_16x16x32_bf16 v[6:9], v[138:141], v[176:179], v[6:9]
	v_mfma_f32_16x16x32_bf16 v[42:45], v[130:133], v[184:187], v[42:45]
	v_mfma_f32_16x16x32_bf16 v[2:5], v[138:141], v[184:187], v[2:5]
	v_mfma_f32_16x16x32_bf16 v[62:65], v[134:137], v[150:153], v[62:65]
	v_mfma_f32_16x16x32_bf16 v[10:13], v[142:145], v[150:153], v[10:13]
	v_mfma_f32_16x16x32_bf16 v[58:61], v[134:137], v[172:175], v[58:61]
	v_mfma_f32_16x16x32_bf16 v[14:17], v[142:145], v[172:175], v[14:17]
	v_mfma_f32_16x16x32_bf16 v[54:57], v[134:137], v[180:183], v[54:57]
	v_mfma_f32_16x16x32_bf16 v[6:9], v[142:145], v[180:183], v[6:9]
	v_mfma_f32_16x16x32_bf16 v[42:45], v[134:137], v[190:193], v[42:45]
	v_mfma_f32_16x16x32_bf16 v[2:5], v[142:145], v[190:193], v[2:5]
	s_barrier
	s_add_u32 s6, s90, 0x40080
	s_addc_u32 s7, s91, 0
	s_add_i32 m0, s39, 0x1c000
	s_nop 0
	global_load_lds_dwordx4 v160, s[6:7]
	s_add_i32 m0, s39, 0x1e000
	s_nop 0
	global_load_lds_dwordx4 v156, s[6:7]
	ds_read_b128 v[130:133], v189
	ds_read_b128 v[134:137], v189 offset:1024
	ds_read_b128 v[138:141], v189 offset:2048
	ds_read_b128 v[142:145], v189 offset:3072
	s_waitcnt vmcnt(6)
	s_barrier
	v_mfma_f32_16x16x32_bf16 v[50:53], v[194:197], v[146:149], v[50:53]
	v_mfma_f32_16x16x32_bf16 v[26:29], v[202:205], v[146:149], v[26:29]
	v_mfma_f32_16x16x32_bf16 v[46:49], v[194:197], v[168:171], v[46:49]
	v_mfma_f32_16x16x32_bf16 v[30:33], v[202:205], v[168:171], v[30:33]
	v_mfma_f32_16x16x32_bf16 v[38:41], v[194:197], v[176:179], v[38:41]
	v_mfma_f32_16x16x32_bf16 v[22:25], v[202:205], v[176:179], v[22:25]
	v_mfma_f32_16x16x32_bf16 v[34:37], v[194:197], v[184:187], v[34:37]
	v_mfma_f32_16x16x32_bf16 v[18:21], v[202:205], v[184:187], v[18:21]
	v_mfma_f32_16x16x32_bf16 v[50:53], v[198:201], v[150:153], v[50:53]
	v_mfma_f32_16x16x32_bf16 v[26:29], v[206:209], v[150:153], v[26:29]
	v_mfma_f32_16x16x32_bf16 v[46:49], v[198:201], v[172:175], v[46:49]
	v_mfma_f32_16x16x32_bf16 v[30:33], v[206:209], v[172:175], v[30:33]
	v_mfma_f32_16x16x32_bf16 v[38:41], v[198:201], v[180:183], v[38:41]
	v_mfma_f32_16x16x32_bf16 v[22:25], v[206:209], v[180:183], v[22:25]
	v_mfma_f32_16x16x32_bf16 v[34:37], v[198:201], v[190:193], v[34:37]
	v_mfma_f32_16x16x32_bf16 v[18:21], v[206:209], v[190:193], v[18:21]
	s_add_i32 s45, s45, 2
	s_add_u32 s28, s28, 0x100
	s_addc_u32 s29, s29, 0
	s_mov_b64 s[6:7], s[88:89]
	s_add_u32 s88, s6, 0x100
	s_addc_u32 s89, s7, 0
	s_cmp_eq_u32 s45, 12
	s_cselect_b32 s93, s17, s89
	s_cselect_b32 s92, s22, s88
	s_cselect_b32 s91, s15, s29
	s_cselect_b32 s90, s23, s28
	s_cmp_gt_u32 s45, 13
	.p2align 3

.LBB0_1089:
	s_add_u32 s34, s84, 0x100
	s_addc_u32 s78, s85, 0
	s_mov_b32 s79, -2
	s_waitcnt lgkmcnt(0)
	s_add_i32 s90, 0, 0x10000
	v_add_u32_e32 v142, s90, v212
	v_add_u32_e32 v189, 0x10000, v212
	ds_read_b128 v[130:133], v142
	ds_read_b128 v[134:137], v142 offset:1024
	ds_read_b128 v[138:141], v142 offset:2048
	ds_read_b128 v[142:145], v142 offset:3072
	s_add_u32 s84, s16, 0x100
	s_addc_u32 s85, s17, 0
	s_cmp_eq_u32 s79, 40
	s_cselect_b32 s89, s5, s85
	s_cselect_b32 s88, s4, s84
	s_cselect_b32 s87, s7, s78
	s_cselect_b32 s86, s6, s34
	v_lshl_add_u64 v[178:179], s[16:17], 0, v[196:197]
	s_add_i32 m0, s39, 0xc000
	ds_read_b128 v[146:149], v213
	ds_read_b128 v[150:153], v213 offset:1024
	ds_read_b128 v[154:157], v213 offset:2048
	ds_read_b128 v[158:161], v213 offset:3072
	ds_read_b128 v[162:165], v213 offset:4096
	ds_read_b128 v[166:169], v213 offset:5120
	ds_read_b128 v[170:173], v213 offset:6144
	ds_read_b128 v[174:177], v213 offset:7168
	global_load_lds_dwordx4 v[178:179], off
	s_add_i32 m0, s39, 0xe000
	v_lshl_add_u64 v[178:179], s[16:17], 0, v[198:199]
	global_load_lds_dwordx4 v[178:179], off
	s_waitcnt lgkmcnt(8)
	s_barrier
	s_waitcnt lgkmcnt(0)
	v_mfma_f32_16x16x32_bf16 v[126:129], v[130:133], v[146:149], 0
	v_mfma_f32_16x16x32_bf16 v[122:125], v[138:141], v[146:149], 0
	v_mfma_f32_16x16x32_bf16 v[110:113], v[130:133], v[154:157], 0
	v_mfma_f32_16x16x32_bf16 v[106:109], v[138:141], v[154:157], 0
	v_mfma_f32_16x16x32_bf16 v[94:97], v[130:133], v[162:165], 0
	v_mfma_f32_16x16x32_bf16 v[90:93], v[138:141], v[162:165], 0
	v_mfma_f32_16x16x32_bf16 v[78:81], v[130:133], v[170:173], 0
	v_mfma_f32_16x16x32_bf16 v[74:77], v[138:141], v[170:173], 0
	v_mfma_f32_16x16x32_bf16 v[126:129], v[134:137], v[150:153], v[126:129]
	v_mfma_f32_16x16x32_bf16 v[122:125], v[142:145], v[150:153], v[122:125]
	v_mfma_f32_16x16x32_bf16 v[110:113], v[134:137], v[158:161], v[110:113]
	v_mfma_f32_16x16x32_bf16 v[106:109], v[142:145], v[158:161], v[106:109]
	v_mfma_f32_16x16x32_bf16 v[94:97], v[134:137], v[166:169], v[94:97]
	v_mfma_f32_16x16x32_bf16 v[90:93], v[142:145], v[166:169], v[90:93]
	v_mfma_f32_16x16x32_bf16 v[78:81], v[134:137], v[174:177], v[78:81]
	v_mfma_f32_16x16x32_bf16 v[74:77], v[142:145], v[174:177], v[74:77]
	s_barrier
	ds_read_b128 v[178:181], v189 offset:16384
	ds_read_b128 v[182:185], v189 offset:17408
	ds_read_b128 v[200:203], v189 offset:18432
	ds_read_b128 v[204:207], v189 offset:19456
	s_add_i32 m0, s38, 0x10000
	s_nop 0
	global_load_lds_dwordx4 v0, s[86:87]
	s_add_i32 m0, s38, 0x12000
	s_nop 0
	global_load_lds_dwordx4 v194, s[86:87]
	s_barrier
	s_waitcnt lgkmcnt(0)
	v_mfma_f32_16x16x32_bf16 v[118:121], v[178:181], v[146:149], 0
	v_mfma_f32_16x16x32_bf16 v[114:117], v[200:203], v[146:149], 0
	v_mfma_f32_16x16x32_bf16 v[102:105], v[178:181], v[154:157], 0
	v_mfma_f32_16x16x32_bf16 v[98:101], v[200:203], v[154:157], 0
	v_mfma_f32_16x16x32_bf16 v[86:89], v[178:181], v[162:165], 0
	v_mfma_f32_16x16x32_bf16 v[82:85], v[200:203], v[162:165], 0
	v_mfma_f32_16x16x32_bf16 v[70:73], v[178:181], v[170:173], 0
	v_mfma_f32_16x16x32_bf16 v[66:69], v[200:203], v[170:173], 0
	v_mfma_f32_16x16x32_bf16 v[118:121], v[182:185], v[150:153], v[118:121]
	v_mfma_f32_16x16x32_bf16 v[114:117], v[204:207], v[150:153], v[114:117]
	v_mfma_f32_16x16x32_bf16 v[102:105], v[182:185], v[158:161], v[102:105]
	v_mfma_f32_16x16x32_bf16 v[98:101], v[204:207], v[158:161], v[98:101]
	v_mfma_f32_16x16x32_bf16 v[86:89], v[182:185], v[166:169], v[86:89]
	v_mfma_f32_16x16x32_bf16 v[82:85], v[204:207], v[166:169], v[82:85]
	v_mfma_f32_16x16x32_bf16 v[70:73], v[182:185], v[174:177], v[70:73]
	v_mfma_f32_16x16x32_bf16 v[66:69], v[204:207], v[174:177], v[66:69]
	s_mov_b32 m0, s39
	s_mov_b64 s[100:101], s[88:89]
	s_barrier
	ds_read_b128 v[146:149], v213 offset:16384
	ds_read_b128 v[150:153], v213 offset:17408
	ds_read_b128 v[154:157], v213 offset:18432
	ds_read_b128 v[158:161], v213 offset:19456
	ds_read_b128 v[162:165], v213 offset:20480
	ds_read_b128 v[166:169], v213 offset:21504
	ds_read_b128 v[170:173], v213 offset:22528
	global_load_lds_dwordx4 v190, s[100:101]
	s_mov_b32 m0, s42
	ds_read_b128 v[174:177], v213 offset:23552
	global_load_lds_dwordx4 v192, s[100:101]
	s_waitcnt vmcnt(10)
	s_barrier
	s_waitcnt lgkmcnt(0)
	v_mfma_f32_16x16x32_bf16 v[62:65], v[130:133], v[146:149], 0
	v_mfma_f32_16x16x32_bf16 v[58:61], v[138:141], v[146:149], 0
	v_mfma_f32_16x16x32_bf16 v[46:49], v[130:133], v[154:157], 0
	v_mfma_f32_16x16x32_bf16 v[42:45], v[138:141], v[154:157], 0
	v_mfma_f32_16x16x32_bf16 v[30:33], v[130:133], v[162:165], 0
	v_mfma_f32_16x16x32_bf16 v[26:29], v[138:141], v[162:165], 0
	v_mfma_f32_16x16x32_bf16 v[14:17], v[130:133], v[170:173], 0
	v_mfma_f32_16x16x32_bf16 v[10:13], v[138:141], v[170:173], 0
	v_mfma_f32_16x16x32_bf16 v[62:65], v[134:137], v[150:153], v[62:65]
	v_mfma_f32_16x16x32_bf16 v[58:61], v[142:145], v[150:153], v[58:61]
	v_mfma_f32_16x16x32_bf16 v[46:49], v[134:137], v[158:161], v[46:49]
	v_mfma_f32_16x16x32_bf16 v[42:45], v[142:145], v[158:161], v[42:45]
	v_mfma_f32_16x16x32_bf16 v[30:33], v[134:137], v[166:169], v[30:33]
	v_mfma_f32_16x16x32_bf16 v[26:29], v[142:145], v[166:169], v[26:29]
	v_mfma_f32_16x16x32_bf16 v[14:17], v[134:137], v[174:177], v[14:17]
	v_mfma_f32_16x16x32_bf16 v[10:13], v[142:145], v[174:177], v[10:13]
	s_barrier
	s_add_u32 s16, s86, 0xb0000
	s_addc_u32 s17, s87, 0
	s_add_i32 m0, s38, 0x14000
	s_nop 0
	global_load_lds_dwordx4 v0, s[16:17]
	s_add_i32 m0, s38, 0x16000
	s_nop 0
	global_load_lds_dwordx4 v194, s[16:17]
	s_add_i32 s90, 0, 0x18000
	v_add_u32_e32 v142, s90, v212
	ds_read_b128 v[130:133], v142
	ds_read_b128 v[134:137], v142 offset:1024
	ds_read_b128 v[138:141], v142 offset:2048
	ds_read_b128 v[142:145], v142 offset:3072
	s_waitcnt vmcnt(6)
	s_barrier
	v_mfma_f32_16x16x32_bf16 v[54:57], v[178:181], v[146:149], 0
	v_mfma_f32_16x16x32_bf16 v[50:53], v[200:203], v[146:149], 0
	v_mfma_f32_16x16x32_bf16 v[38:41], v[178:181], v[154:157], 0
	v_mfma_f32_16x16x32_bf16 v[34:37], v[200:203], v[154:157], 0
	v_mfma_f32_16x16x32_bf16 v[22:25], v[178:181], v[162:165], 0
	v_mfma_f32_16x16x32_bf16 v[18:21], v[200:203], v[162:165], 0
	v_mfma_f32_16x16x32_bf16 v[6:9], v[178:181], v[170:173], 0
	v_mfma_f32_16x16x32_bf16 v[2:5], v[200:203], v[170:173], 0
	v_mfma_f32_16x16x32_bf16 v[54:57], v[182:185], v[150:153], v[54:57]
	v_mfma_f32_16x16x32_bf16 v[50:53], v[204:207], v[150:153], v[50:53]
	v_mfma_f32_16x16x32_bf16 v[38:41], v[182:185], v[158:161], v[38:41]
	v_mfma_f32_16x16x32_bf16 v[34:37], v[204:207], v[158:161], v[34:37]
	v_mfma_f32_16x16x32_bf16 v[22:25], v[182:185], v[166:169], v[22:25]
	v_mfma_f32_16x16x32_bf16 v[18:21], v[204:207], v[166:169], v[18:21]
	v_mfma_f32_16x16x32_bf16 v[6:9], v[182:185], v[174:177], v[6:9]
	v_mfma_f32_16x16x32_bf16 v[2:5], v[204:207], v[174:177], v[2:5]
	s_barrier
	s_add_u32 s16, s88, 0xb0000
	s_addc_u32 s17, s89, 0
	s_mov_b32 m0, s43
	ds_read_b128 v[146:149], v213 offset:32768
	ds_read_b128 v[150:153], v213 offset:33792
	ds_read_b128 v[154:157], v213 offset:34816
	ds_read_b128 v[158:161], v213 offset:35840
	ds_read_b128 v[162:165], v213 offset:36864
	ds_read_b128 v[166:169], v213 offset:37888
	ds_read_b128 v[170:173], v213 offset:38912
	global_load_lds_dwordx4 v190, s[16:17]
	s_mov_b32 m0, s44
	ds_read_b128 v[174:177], v213 offset:39936
	global_load_lds_dwordx4 v192, s[16:17]
	s_waitcnt lgkmcnt(8)
	s_barrier
	s_waitcnt lgkmcnt(0)
	v_mfma_f32_16x16x32_bf16 v[126:129], v[130:133], v[146:149], v[126:129]
	v_mfma_f32_16x16x32_bf16 v[122:125], v[138:141], v[146:149], v[122:125]
	v_mfma_f32_16x16x32_bf16 v[110:113], v[130:133], v[154:157], v[110:113]
	v_mfma_f32_16x16x32_bf16 v[106:109], v[138:141], v[154:157], v[106:109]
	v_mfma_f32_16x16x32_bf16 v[94:97], v[130:133], v[162:165], v[94:97]
	v_mfma_f32_16x16x32_bf16 v[90:93], v[138:141], v[162:165], v[90:93]
	v_mfma_f32_16x16x32_bf16 v[78:81], v[130:133], v[170:173], v[78:81]
	v_mfma_f32_16x16x32_bf16 v[74:77], v[138:141], v[170:173], v[74:77]
	v_mfma_f32_16x16x32_bf16 v[126:129], v[134:137], v[150:153], v[126:129]
	v_mfma_f32_16x16x32_bf16 v[122:125], v[142:145], v[150:153], v[122:125]
	v_mfma_f32_16x16x32_bf16 v[110:113], v[134:137], v[158:161], v[110:113]
	v_mfma_f32_16x16x32_bf16 v[106:109], v[142:145], v[158:161], v[106:109]
	v_mfma_f32_16x16x32_bf16 v[94:97], v[134:137], v[166:169], v[94:97]
	v_mfma_f32_16x16x32_bf16 v[90:93], v[142:145], v[166:169], v[90:93]
	v_mfma_f32_16x16x32_bf16 v[78:81], v[134:137], v[174:177], v[78:81]
	v_mfma_f32_16x16x32_bf16 v[74:77], v[142:145], v[174:177], v[74:77]
	s_barrier
	s_add_i32 s88, 0, 0x1c000
	v_add_u32_e32 v204, s88, v212
	s_add_i32 m0, s38, 0x18000
	ds_read_b128 v[178:181], v204
	ds_read_b128 v[182:185], v204 offset:1024
	ds_read_b128 v[200:203], v204 offset:2048
	ds_read_b128 v[204:207], v204 offset:3072
	s_add_u32 s98, s86, s40
	s_addc_u32 s99, s87, s41
	global_load_lds_dwordx4 v0, s[98:99]
	s_add_i32 m0, s38, 0x1a000
	s_nop 0
	global_load_lds_dwordx4 v194, s[98:99]
	s_barrier
	s_waitcnt lgkmcnt(0)
	v_mfma_f32_16x16x32_bf16 v[118:121], v[178:181], v[146:149], v[118:121]
	v_mfma_f32_16x16x32_bf16 v[114:117], v[200:203], v[146:149], v[114:117]
	v_mfma_f32_16x16x32_bf16 v[102:105], v[178:181], v[154:157], v[102:105]
	v_mfma_f32_16x16x32_bf16 v[98:101], v[200:203], v[154:157], v[98:101]
	v_mfma_f32_16x16x32_bf16 v[86:89], v[178:181], v[162:165], v[86:89]
	v_mfma_f32_16x16x32_bf16 v[82:85], v[200:203], v[162:165], v[82:85]
	v_mfma_f32_16x16x32_bf16 v[70:73], v[178:181], v[170:173], v[70:73]
	v_mfma_f32_16x16x32_bf16 v[66:69], v[200:203], v[170:173], v[66:69]
	v_mfma_f32_16x16x32_bf16 v[118:121], v[182:185], v[150:153], v[118:121]
	v_mfma_f32_16x16x32_bf16 v[114:117], v[204:207], v[150:153], v[114:117]
	v_mfma_f32_16x16x32_bf16 v[102:105], v[182:185], v[158:161], v[102:105]
	v_mfma_f32_16x16x32_bf16 v[98:101], v[204:207], v[158:161], v[98:101]
	v_mfma_f32_16x16x32_bf16 v[86:89], v[182:185], v[166:169], v[86:89]
	v_mfma_f32_16x16x32_bf16 v[82:85], v[204:207], v[166:169], v[82:85]
	v_mfma_f32_16x16x32_bf16 v[70:73], v[182:185], v[174:177], v[70:73]
	v_mfma_f32_16x16x32_bf16 v[66:69], v[204:207], v[174:177], v[66:69]
	s_mov_b32 m0, s60
	s_barrier
	ds_read_b128 v[146:149], v213 offset:49152
	ds_read_b128 v[150:153], v213 offset:50176
	ds_read_b128 v[154:157], v213 offset:51200
	ds_read_b128 v[158:161], v213 offset:52224
	ds_read_b128 v[162:165], v213 offset:53248
	ds_read_b128 v[166:169], v213 offset:54272
	ds_read_b128 v[170:173], v213 offset:55296
	ds_read_b128 v[174:177], v213 offset:56320
	s_add_u32 s98, s100, s40
	s_addc_u32 s99, s101, s41
	global_load_lds_dwordx4 v190, s[98:99]
	s_mov_b32 m0, s61
	s_nop 0
	global_load_lds_dwordx4 v192, s[98:99]
	s_waitcnt vmcnt(10)
	s_barrier
	s_waitcnt lgkmcnt(0)
	v_mfma_f32_16x16x32_bf16 v[62:65], v[130:133], v[146:149], v[62:65]
	v_mfma_f32_16x16x32_bf16 v[58:61], v[138:141], v[146:149], v[58:61]
	v_mfma_f32_16x16x32_bf16 v[46:49], v[130:133], v[154:157], v[46:49]
	v_mfma_f32_16x16x32_bf16 v[42:45], v[138:141], v[154:157], v[42:45]
	v_mfma_f32_16x16x32_bf16 v[30:33], v[130:133], v[162:165], v[30:33]
	v_mfma_f32_16x16x32_bf16 v[26:29], v[138:141], v[162:165], v[26:29]
	v_mfma_f32_16x16x32_bf16 v[14:17], v[130:133], v[170:173], v[14:17]
	v_mfma_f32_16x16x32_bf16 v[10:13], v[138:141], v[170:173], v[10:13]
	v_mfma_f32_16x16x32_bf16 v[62:65], v[134:137], v[150:153], v[62:65]
	v_mfma_f32_16x16x32_bf16 v[58:61], v[142:145], v[150:153], v[58:61]
	v_mfma_f32_16x16x32_bf16 v[46:49], v[134:137], v[158:161], v[46:49]
	v_mfma_f32_16x16x32_bf16 v[42:45], v[142:145], v[158:161], v[42:45]
	v_mfma_f32_16x16x32_bf16 v[30:33], v[134:137], v[166:169], v[30:33]
	v_mfma_f32_16x16x32_bf16 v[26:29], v[142:145], v[166:169], v[26:29]
	v_mfma_f32_16x16x32_bf16 v[14:17], v[134:137], v[174:177], v[14:17]
	v_mfma_f32_16x16x32_bf16 v[10:13], v[142:145], v[174:177], v[10:13]
	s_barrier
	s_add_u32 s16, s86, 0xb0080
	s_addc_u32 s17, s87, 0
	s_add_i32 m0, s38, 0x1c000
	s_nop 0
	global_load_lds_dwordx4 v0, s[16:17]
	s_add_i32 m0, s38, 0x1e000
	s_nop 0
	global_load_lds_dwordx4 v194, s[16:17]
	ds_read_b128 v[130:133], v189
	ds_read_b128 v[134:137], v189 offset:1024
	ds_read_b128 v[138:141], v189 offset:2048
	ds_read_b128 v[142:145], v189 offset:3072
	s_waitcnt vmcnt(6)
	s_barrier
	v_mfma_f32_16x16x32_bf16 v[54:57], v[178:181], v[146:149], v[54:57]
	v_mfma_f32_16x16x32_bf16 v[50:53], v[200:203], v[146:149], v[50:53]
	v_mfma_f32_16x16x32_bf16 v[38:41], v[178:181], v[154:157], v[38:41]
	v_mfma_f32_16x16x32_bf16 v[34:37], v[200:203], v[154:157], v[34:37]
	v_mfma_f32_16x16x32_bf16 v[22:25], v[178:181], v[162:165], v[22:25]
	v_mfma_f32_16x16x32_bf16 v[18:21], v[200:203], v[162:165], v[18:21]
	v_mfma_f32_16x16x32_bf16 v[6:9], v[178:181], v[170:173], v[6:9]
	v_mfma_f32_16x16x32_bf16 v[2:5], v[200:203], v[170:173], v[2:5]
	v_mfma_f32_16x16x32_bf16 v[54:57], v[182:185], v[150:153], v[54:57]
	v_mfma_f32_16x16x32_bf16 v[50:53], v[204:207], v[150:153], v[50:53]
	v_mfma_f32_16x16x32_bf16 v[38:41], v[182:185], v[158:161], v[38:41]
	v_mfma_f32_16x16x32_bf16 v[34:37], v[204:207], v[158:161], v[34:37]
	v_mfma_f32_16x16x32_bf16 v[22:25], v[182:185], v[166:169], v[22:25]
	v_mfma_f32_16x16x32_bf16 v[18:21], v[204:207], v[166:169], v[18:21]
	v_mfma_f32_16x16x32_bf16 v[6:9], v[182:185], v[174:177], v[6:9]
	v_mfma_f32_16x16x32_bf16 v[2:5], v[204:207], v[174:177], v[2:5]
	s_add_i32 s79, s79, 2
	s_add_u32 s34, s34, 0x100
	s_addc_u32 s78, s78, 0
	s_mov_b64 s[16:17], s[84:85]
	s_add_u32 s84, s16, 0x100
	s_addc_u32 s85, s17, 0
	s_cmp_eq_u32 s79, 40
	s_cselect_b32 s89, s5, s85
	s_cselect_b32 s88, s4, s84
	s_cselect_b32 s87, s7, s78
	s_cselect_b32 s86, s6, s34
	s_cmp_gt_u32 s79, 41
	.p2align 3

.LBB0_1208:
	s_ashr_i32 s13, s12, 31
	v_cmp_lt_i64_e32 vcc, s[14:15], v[230:231]
	s_lshl_b64 s[14:15], s[12:13], 19
	s_add_u32 s14, s80, s14
	s_addc_u32 s15, s81, s15
	s_and_b64 s[16:17], vcc, exec
	s_cselect_b32 s13, s15, s89
	s_cselect_b32 s22, s14, s88
	s_ashr_i32 s7, s6, 31
	s_lshl_b64 s[16:17], s[6:7], 19
	s_add_u32 s16, s36, s16
	s_addc_u32 s17, s37, s17
	s_and_b64 s[92:93], vcc, exec
	s_cselect_b32 s7, s17, s91
	s_cselect_b32 s23, s16, s90
	s_add_u32 s88, s88, 0x40080
	s_addc_u32 s89, s89, 0
	s_add_u32 s34, s90, 0x100
	s_addc_u32 s79, s91, 0
	s_mov_b32 s85, -2
	s_waitcnt lgkmcnt(0)
	s_add_i32 s94, 0, 0x10000
	v_add_u32_e32 v0, s94, v170
	v_add_u32_e32 v189, 0x10000, v170
	ds_read_b128 v[130:133], v0
	ds_read_b128 v[134:137], v0 offset:1024
	ds_read_b128 v[138:141], v0 offset:2048
	ds_read_b128 v[142:145], v0 offset:3072
	s_add_u32 s87, s88, 0xfffc0080
	s_addc_u32 s90, s89, -1
	s_cmp_eq_u32 s85, 12
	s_cselect_b32 s93, s13, s90
	s_cselect_b32 s92, s22, s87
	s_cselect_b32 s91, s7, s79
	s_cselect_b32 s90, s23, s34
	s_waitcnt lgkmcnt(0)
	s_add_i32 m0, s39, 0xc000
	ds_read_b128 v[158:161], v171
	ds_read_b128 v[162:165], v171 offset:1024
	ds_read_b128 v[166:169], v171 offset:2048
	ds_read_b128 v[172:175], v171 offset:3072
	ds_read_b128 v[176:179], v171 offset:4096
	ds_read_b128 v[180:183], v171 offset:5120
	ds_read_b128 v[184:187], v171 offset:6144
	global_load_lds_dwordx4 v154, s[88:89]
	s_add_i32 m0, s39, 0xe000
	ds_read_b128 v[190:193], v171 offset:7168
	global_load_lds_dwordx4 v156, s[88:89]
	s_waitcnt lgkmcnt(8)
	s_barrier
	s_waitcnt lgkmcnt(0)
	v_mfma_f32_16x16x32_bf16 v[126:129], v[130:133], v[158:161], 0
	v_mfma_f32_16x16x32_bf16 v[122:125], v[138:141], v[158:161], 0
	v_mfma_f32_16x16x32_bf16 v[110:113], v[130:133], v[166:169], 0
	v_mfma_f32_16x16x32_bf16 v[106:109], v[138:141], v[166:169], 0
	v_mfma_f32_16x16x32_bf16 v[94:97], v[130:133], v[176:179], 0
	v_mfma_f32_16x16x32_bf16 v[90:93], v[138:141], v[176:179], 0
	v_mfma_f32_16x16x32_bf16 v[78:81], v[130:133], v[184:187], 0
	v_mfma_f32_16x16x32_bf16 v[74:77], v[138:141], v[184:187], 0
	v_mfma_f32_16x16x32_bf16 v[126:129], v[134:137], v[162:165], v[126:129]
	v_mfma_f32_16x16x32_bf16 v[122:125], v[142:145], v[162:165], v[122:125]
	v_mfma_f32_16x16x32_bf16 v[110:113], v[134:137], v[172:175], v[110:113]
	v_mfma_f32_16x16x32_bf16 v[106:109], v[142:145], v[172:175], v[106:109]
	v_mfma_f32_16x16x32_bf16 v[94:97], v[134:137], v[180:183], v[94:97]
	v_mfma_f32_16x16x32_bf16 v[90:93], v[142:145], v[180:183], v[90:93]
	v_mfma_f32_16x16x32_bf16 v[78:81], v[134:137], v[190:193], v[78:81]
	v_mfma_f32_16x16x32_bf16 v[74:77], v[142:145], v[190:193], v[74:77]
	s_barrier
	s_add_i32 m0, s38, 0x10000
	ds_read_b128 v[194:197], v189 offset:16384
	ds_read_b128 v[198:201], v189 offset:17408
	ds_read_b128 v[202:205], v189 offset:18432
	global_load_lds_dwordx4 v148, s[90:91]
	s_add_i32 m0, s38, 0x12000
	ds_read_b128 v[206:209], v189 offset:19456
	global_load_lds_dwordx4 v152, s[90:91]
	s_barrier
	s_waitcnt lgkmcnt(0)
	v_mfma_f32_16x16x32_bf16 v[118:121], v[194:197], v[158:161], 0
	v_mfma_f32_16x16x32_bf16 v[114:117], v[202:205], v[158:161], 0
	v_mfma_f32_16x16x32_bf16 v[102:105], v[194:197], v[166:169], 0
	v_mfma_f32_16x16x32_bf16 v[98:101], v[202:205], v[166:169], 0
	v_mfma_f32_16x16x32_bf16 v[86:89], v[194:197], v[176:179], 0
	v_mfma_f32_16x16x32_bf16 v[82:85], v[202:205], v[176:179], 0
	v_mfma_f32_16x16x32_bf16 v[70:73], v[194:197], v[184:187], 0
	v_mfma_f32_16x16x32_bf16 v[66:69], v[202:205], v[184:187], 0
	v_mfma_f32_16x16x32_bf16 v[118:121], v[198:201], v[162:165], v[118:121]
	v_mfma_f32_16x16x32_bf16 v[114:117], v[206:209], v[162:165], v[114:117]
	v_mfma_f32_16x16x32_bf16 v[102:105], v[198:201], v[172:175], v[102:105]
	v_mfma_f32_16x16x32_bf16 v[98:101], v[206:209], v[172:175], v[98:101]
	v_mfma_f32_16x16x32_bf16 v[86:89], v[198:201], v[180:183], v[86:89]
	v_mfma_f32_16x16x32_bf16 v[82:85], v[206:209], v[180:183], v[82:85]
	v_mfma_f32_16x16x32_bf16 v[70:73], v[198:201], v[190:193], v[70:73]
	v_mfma_f32_16x16x32_bf16 v[66:69], v[206:209], v[190:193], v[66:69]
	s_mov_b32 m0, s39
	s_mov_b64 s[100:101], s[92:93]
	s_barrier
	ds_read_b128 v[158:161], v171 offset:16384
	ds_read_b128 v[162:165], v171 offset:17408
	ds_read_b128 v[166:169], v171 offset:18432
	ds_read_b128 v[172:175], v171 offset:19456
	ds_read_b128 v[176:179], v171 offset:20480
	ds_read_b128 v[180:183], v171 offset:21504
	ds_read_b128 v[184:187], v171 offset:22528
	global_load_lds_dwordx4 v146, s[100:101]
	s_mov_b32 m0, s42
	ds_read_b128 v[190:193], v171 offset:23552
	global_load_lds_dwordx4 v150, s[100:101]
	s_waitcnt vmcnt(10)
	s_barrier
	s_waitcnt lgkmcnt(0)
	v_mfma_f32_16x16x32_bf16 v[62:65], v[130:133], v[158:161], 0
	v_mfma_f32_16x16x32_bf16 v[58:61], v[138:141], v[158:161], 0
	v_mfma_f32_16x16x32_bf16 v[46:49], v[130:133], v[166:169], 0
	v_mfma_f32_16x16x32_bf16 v[42:45], v[138:141], v[166:169], 0
	v_mfma_f32_16x16x32_bf16 v[30:33], v[130:133], v[176:179], 0
	v_mfma_f32_16x16x32_bf16 v[26:29], v[138:141], v[176:179], 0
	v_mfma_f32_16x16x32_bf16 v[14:17], v[130:133], v[184:187], 0
	v_mfma_f32_16x16x32_bf16 v[10:13], v[138:141], v[184:187], 0
	v_mfma_f32_16x16x32_bf16 v[62:65], v[134:137], v[162:165], v[62:65]
	v_mfma_f32_16x16x32_bf16 v[58:61], v[142:145], v[162:165], v[58:61]
	v_mfma_f32_16x16x32_bf16 v[46:49], v[134:137], v[172:175], v[46:49]
	v_mfma_f32_16x16x32_bf16 v[42:45], v[142:145], v[172:175], v[42:45]
	v_mfma_f32_16x16x32_bf16 v[30:33], v[134:137], v[180:183], v[30:33]
	v_mfma_f32_16x16x32_bf16 v[26:29], v[142:145], v[180:183], v[26:29]
	v_mfma_f32_16x16x32_bf16 v[14:17], v[134:137], v[190:193], v[14:17]
	v_mfma_f32_16x16x32_bf16 v[10:13], v[142:145], v[190:193], v[10:13]
	s_barrier
	s_add_u32 s94, s90, 0x40000
	s_addc_u32 s95, s91, 0
	s_add_i32 m0, s38, 0x14000
	s_nop 0
	global_load_lds_dwordx4 v148, s[94:95]
	s_add_i32 m0, s38, 0x16000
	s_nop 0
	global_load_lds_dwordx4 v152, s[94:95]
	ds_read_b128 v[130:133], v189 offset:32768
	ds_read_b128 v[134:137], v189 offset:33792
	ds_read_b128 v[138:141], v189 offset:34816
	ds_read_b128 v[142:145], v189 offset:35840
	s_waitcnt vmcnt(6)
	s_barrier
	v_mfma_f32_16x16x32_bf16 v[54:57], v[194:197], v[158:161], 0
	v_mfma_f32_16x16x32_bf16 v[50:53], v[202:205], v[158:161], 0
	v_mfma_f32_16x16x32_bf16 v[38:41], v[194:197], v[166:169], 0
	v_mfma_f32_16x16x32_bf16 v[34:37], v[202:205], v[166:169], 0
	v_mfma_f32_16x16x32_bf16 v[22:25], v[194:197], v[176:179], 0
	v_mfma_f32_16x16x32_bf16 v[18:21], v[202:205], v[176:179], 0
	v_mfma_f32_16x16x32_bf16 v[6:9], v[194:197], v[184:187], 0
	v_mfma_f32_16x16x32_bf16 v[2:5], v[202:205], v[184:187], 0
	v_mfma_f32_16x16x32_bf16 v[54:57], v[198:201], v[162:165], v[54:57]
	v_mfma_f32_16x16x32_bf16 v[50:53], v[206:209], v[162:165], v[50:53]
	v_mfma_f32_16x16x32_bf16 v[38:41], v[198:201], v[172:175], v[38:41]
	v_mfma_f32_16x16x32_bf16 v[34:37], v[206:209], v[172:175], v[34:37]
	v_mfma_f32_16x16x32_bf16 v[22:25], v[198:201], v[180:183], v[22:25]
	v_mfma_f32_16x16x32_bf16 v[18:21], v[206:209], v[180:183], v[18:21]
	v_mfma_f32_16x16x32_bf16 v[6:9], v[198:201], v[190:193], v[6:9]
	v_mfma_f32_16x16x32_bf16 v[2:5], v[206:209], v[190:193], v[2:5]
	s_barrier
	s_add_u32 s92, s92, 0x40000
	s_addc_u32 s93, s93, 0
	s_mov_b32 m0, s43
	ds_read_b128 v[158:161], v171 offset:32768
	ds_read_b128 v[162:165], v171 offset:33792
	ds_read_b128 v[166:169], v171 offset:34816
	ds_read_b128 v[172:175], v171 offset:35840
	ds_read_b128 v[176:179], v171 offset:36864
	ds_read_b128 v[180:183], v171 offset:37888
	ds_read_b128 v[184:187], v171 offset:38912
	global_load_lds_dwordx4 v146, s[92:93]
	s_mov_b32 m0, s44
	ds_read_b128 v[190:193], v171 offset:39936
	global_load_lds_dwordx4 v150, s[92:93]
	s_waitcnt lgkmcnt(8)
	s_barrier
	s_waitcnt lgkmcnt(0)
	v_mfma_f32_16x16x32_bf16 v[126:129], v[130:133], v[158:161], v[126:129]
	v_mfma_f32_16x16x32_bf16 v[122:125], v[138:141], v[158:161], v[122:125]
	v_mfma_f32_16x16x32_bf16 v[110:113], v[130:133], v[166:169], v[110:113]
	v_mfma_f32_16x16x32_bf16 v[106:109], v[138:141], v[166:169], v[106:109]
	v_mfma_f32_16x16x32_bf16 v[94:97], v[130:133], v[176:179], v[94:97]
	v_mfma_f32_16x16x32_bf16 v[90:93], v[138:141], v[176:179], v[90:93]
	v_mfma_f32_16x16x32_bf16 v[78:81], v[130:133], v[184:187], v[78:81]
	v_mfma_f32_16x16x32_bf16 v[74:77], v[138:141], v[184:187], v[74:77]
	v_mfma_f32_16x16x32_bf16 v[126:129], v[134:137], v[162:165], v[126:129]
	v_mfma_f32_16x16x32_bf16 v[122:125], v[142:145], v[162:165], v[122:125]
	v_mfma_f32_16x16x32_bf16 v[110:113], v[134:137], v[172:175], v[110:113]
	v_mfma_f32_16x16x32_bf16 v[106:109], v[142:145], v[172:175], v[106:109]
	v_mfma_f32_16x16x32_bf16 v[94:97], v[134:137], v[180:183], v[94:97]
	v_mfma_f32_16x16x32_bf16 v[90:93], v[142:145], v[180:183], v[90:93]
	v_mfma_f32_16x16x32_bf16 v[78:81], v[134:137], v[190:193], v[78:81]
	v_mfma_f32_16x16x32_bf16 v[74:77], v[142:145], v[190:193], v[74:77]
	s_barrier
	s_add_i32 m0, s38, 0x18000
	ds_read_b128 v[194:197], v189 offset:49152
	ds_read_b128 v[198:201], v189 offset:50176
	ds_read_b128 v[202:205], v189 offset:51200
	ds_read_b128 v[206:209], v189 offset:52224
	s_add_u32 s98, s90, s40
	s_addc_u32 s99, s91, s41
	global_load_lds_dwordx4 v148, s[98:99]
	s_add_i32 m0, s38, 0x1a000
	s_nop 0
	global_load_lds_dwordx4 v152, s[98:99]
	s_barrier
	s_waitcnt lgkmcnt(0)
	v_mfma_f32_16x16x32_bf16 v[118:121], v[194:197], v[158:161], v[118:121]
	v_mfma_f32_16x16x32_bf16 v[114:117], v[202:205], v[158:161], v[114:117]
	v_mfma_f32_16x16x32_bf16 v[102:105], v[194:197], v[166:169], v[102:105]
	v_mfma_f32_16x16x32_bf16 v[98:101], v[202:205], v[166:169], v[98:101]
	v_mfma_f32_16x16x32_bf16 v[86:89], v[194:197], v[176:179], v[86:89]
	v_mfma_f32_16x16x32_bf16 v[82:85], v[202:205], v[176:179], v[82:85]
	v_mfma_f32_16x16x32_bf16 v[70:73], v[194:197], v[184:187], v[70:73]
	v_mfma_f32_16x16x32_bf16 v[66:69], v[202:205], v[184:187], v[66:69]
	v_mfma_f32_16x16x32_bf16 v[118:121], v[198:201], v[162:165], v[118:121]
	v_mfma_f32_16x16x32_bf16 v[114:117], v[206:209], v[162:165], v[114:117]
	v_mfma_f32_16x16x32_bf16 v[102:105], v[198:201], v[172:175], v[102:105]
	v_mfma_f32_16x16x32_bf16 v[98:101], v[206:209], v[172:175], v[98:101]
	v_mfma_f32_16x16x32_bf16 v[86:89], v[198:201], v[180:183], v[86:89]
	v_mfma_f32_16x16x32_bf16 v[82:85], v[206:209], v[180:183], v[82:85]
	v_mfma_f32_16x16x32_bf16 v[70:73], v[198:201], v[190:193], v[70:73]
	v_mfma_f32_16x16x32_bf16 v[66:69], v[206:209], v[190:193], v[66:69]
	s_mov_b32 m0, s60
	s_barrier
	ds_read_b128 v[158:161], v171 offset:49152
	ds_read_b128 v[162:165], v171 offset:50176
	ds_read_b128 v[166:169], v171 offset:51200
	ds_read_b128 v[172:175], v171 offset:52224
	ds_read_b128 v[176:179], v171 offset:53248
	ds_read_b128 v[180:183], v171 offset:54272
	ds_read_b128 v[184:187], v171 offset:55296
	ds_read_b128 v[190:193], v171 offset:56320
	s_add_u32 s98, s100, s40
	s_addc_u32 s99, s101, s41
	global_load_lds_dwordx4 v146, s[98:99]
	s_mov_b32 m0, s61
	s_nop 0
	global_load_lds_dwordx4 v150, s[98:99]
	s_waitcnt vmcnt(10)
	s_barrier
	s_waitcnt lgkmcnt(0)
	v_mfma_f32_16x16x32_bf16 v[62:65], v[130:133], v[158:161], v[62:65]
	v_mfma_f32_16x16x32_bf16 v[58:61], v[138:141], v[158:161], v[58:61]
	v_mfma_f32_16x16x32_bf16 v[46:49], v[130:133], v[166:169], v[46:49]
	v_mfma_f32_16x16x32_bf16 v[42:45], v[138:141], v[166:169], v[42:45]
	v_mfma_f32_16x16x32_bf16 v[30:33], v[130:133], v[176:179], v[30:33]
	v_mfma_f32_16x16x32_bf16 v[26:29], v[138:141], v[176:179], v[26:29]
	v_mfma_f32_16x16x32_bf16 v[14:17], v[130:133], v[184:187], v[14:17]
	v_mfma_f32_16x16x32_bf16 v[10:13], v[138:141], v[184:187], v[10:13]
	v_mfma_f32_16x16x32_bf16 v[62:65], v[134:137], v[162:165], v[62:65]
	v_mfma_f32_16x16x32_bf16 v[58:61], v[142:145], v[162:165], v[58:61]
	v_mfma_f32_16x16x32_bf16 v[46:49], v[134:137], v[172:175], v[46:49]
	v_mfma_f32_16x16x32_bf16 v[42:45], v[142:145], v[172:175], v[42:45]
	v_mfma_f32_16x16x32_bf16 v[30:33], v[134:137], v[180:183], v[30:33]
	v_mfma_f32_16x16x32_bf16 v[26:29], v[142:145], v[180:183], v[26:29]
	v_mfma_f32_16x16x32_bf16 v[14:17], v[134:137], v[190:193], v[14:17]
	v_mfma_f32_16x16x32_bf16 v[10:13], v[142:145], v[190:193], v[10:13]
	s_barrier
	s_add_u32 s90, s90, 0x40080
	s_addc_u32 s91, s91, 0
	s_add_i32 m0, s38, 0x1c000
	s_nop 0
	global_load_lds_dwordx4 v148, s[90:91]
	s_add_i32 m0, s38, 0x1e000
	s_nop 0
	global_load_lds_dwordx4 v152, s[90:91]
	ds_read_b128 v[130:133], v189
	ds_read_b128 v[134:137], v189 offset:1024
	ds_read_b128 v[138:141], v189 offset:2048
	ds_read_b128 v[142:145], v189 offset:3072
	s_waitcnt vmcnt(6)
	s_barrier
	v_mfma_f32_16x16x32_bf16 v[54:57], v[194:197], v[158:161], v[54:57]
	v_mfma_f32_16x16x32_bf16 v[50:53], v[202:205], v[158:161], v[50:53]
	v_mfma_f32_16x16x32_bf16 v[38:41], v[194:197], v[166:169], v[38:41]
	v_mfma_f32_16x16x32_bf16 v[34:37], v[202:205], v[166:169], v[34:37]
	v_mfma_f32_16x16x32_bf16 v[22:25], v[194:197], v[176:179], v[22:25]
	v_mfma_f32_16x16x32_bf16 v[18:21], v[202:205], v[176:179], v[18:21]
	v_mfma_f32_16x16x32_bf16 v[6:9], v[194:197], v[184:187], v[6:9]
	v_mfma_f32_16x16x32_bf16 v[2:5], v[202:205], v[184:187], v[2:5]
	v_mfma_f32_16x16x32_bf16 v[54:57], v[198:201], v[162:165], v[54:57]
	v_mfma_f32_16x16x32_bf16 v[50:53], v[206:209], v[162:165], v[50:53]
	v_mfma_f32_16x16x32_bf16 v[38:41], v[198:201], v[172:175], v[38:41]
	v_mfma_f32_16x16x32_bf16 v[34:37], v[206:209], v[172:175], v[34:37]
	v_mfma_f32_16x16x32_bf16 v[22:25], v[198:201], v[180:183], v[22:25]
	v_mfma_f32_16x16x32_bf16 v[18:21], v[206:209], v[180:183], v[18:21]
	v_mfma_f32_16x16x32_bf16 v[6:9], v[198:201], v[190:193], v[6:9]
	v_mfma_f32_16x16x32_bf16 v[2:5], v[206:209], v[190:193], v[2:5]
	s_add_i32 s85, s85, 2
	s_add_u32 s88, s88, 0x100
	s_addc_u32 s89, s89, 0
	s_add_u32 s34, s34, 0x100
	s_addc_u32 s79, s79, 0
	s_add_u32 s87, s88, 0xfffc0080
	s_addc_u32 s90, s89, -1
	s_cmp_eq_u32 s85, 12
	s_cselect_b32 s93, s13, s90
	s_cselect_b32 s92, s22, s87
	s_cselect_b32 s91, s7, s79
	s_cselect_b32 s90, s23, s34
	s_cmp_gt_u32 s85, 13
	.p2align 3
